# GEMM compute segments: removed the s_setprio 0/1 pair between the two 16-MFMA blocks and the redundant lgkmcnt(0) before the first MFMA (outer raise/lower kept); plus pipelined census loads
# speedup vs baseline: 1.0054x; 1.0054x over previous
; #define PG8_STAGE(bufoff, gbase, voff) do { _Pragma("unroll") for (int _i = 0; _i < 2; ++_i) \
;         __builtin_amdgcn_global_load_lds((const unsigned*)((const char*)(gbase) + (voff)[_i]), (PG8_LAS unsigned*)(lds + (bufoff) + ldsw + _i * 8192), 16, 0, 0); } while (0)
; #define PG8_LDA(dst, b, h) do { _Pragma("unroll") for (int m = 0; m < 4; ++m) _Pragma("unroll") for (int k = 0; k < 2; ++k) dst[m][k] = *(const PG8_LAS bf16x8*)(lds + PG8_SA(b, h) + aoff + m * 2048 + k * 1024); } while (0)
; #define PG8_LDB(dst, b, h) do { _Pragma("unroll") for (int n = 0; n < 2; ++n) _Pragma("unroll") for (int k = 0; k < 2; ++k) dst[n][k] = *(const PG8_LAS bf16x8*)(lds + PG8_SB(b, h) + boff + n * 2048 + k * 1024); } while (0)
; #define PG8_MMA(ai, bj, At, Bt) do { __builtin_amdgcn_s_setprio(1); _Pragma("unroll") for (int m = 0; m < 4; ++m) _Pragma("unroll") for (int n = 0; n < 2; ++n) _Pragma("unroll") for (int k = 0; k < 2; ++k) \
;         acc[ai][bj][m][n] = __builtin_amdgcn_mfma_f32_16x16x32_bf16(Bt[n][k], At[m][k], acc[ai][bj][m][n], 0, 0, 0); __builtin_amdgcn_s_setprio(0); } while (0)
; #define PG8_WAIT_V(n) asm volatile("s_waitcnt vmcnt(" #n ")" ::: "memory")
; #define PG8_WAIT_L(n) asm volatile("s_waitcnt lgkmcnt(" #n ")" ::: "memory")
; #define PG8_BAR __builtin_amdgcn_s_barrier()
; #define PG8_SCHED __builtin_amdgcn_sched_barrier(0)
; template <class Epi, class Sched, bool ALIGN_EPI = false, bool SP2 = false>
; __device__ __forceinline__ void gemm_phase(PG8_LAS unsigned char* lds, const Gemm g, const Sched& S, const Epi& E) {
;     ...
;             PG8_LDB(B0, 0, 0); PG8_LDB(B1, 0, 1); PG8_SCHED; PG8_LDA(At, 0, 0); PG8_STAGE(PG8_SA(1, 1), a1 + hstep, voffA);
;             PG8_WAIT_V(8); PG8_WAIT_L(0); PG8_BAR; PG8_MMA(0, 0, At, B0); PG8_MMA(0, 1, At, B1); PG8_BAR; PG8_SCHED;
;             PG8_LDA(At, 0, 1); PG8_STAGE(PG8_SB(0, 0), b2, voffB); PG8_STAGE(PG8_SB(0, 1), b2 + hstep, voffB); PG8_STAGE(PG8_SA(0, 0), a2, voffA);
.LBB0_265:
	s_add_u32 s10, s16, 0xfff80080
	s_addc_u32 s11, s17, -1
	s_add_i32 s27, 0, 0x10000
	s_cmp_eq_u32 s23, 28
	s_cselect_b32 s51, s5, s11
	s_cselect_b32 s50, s7, s10
	s_cselect_b32 s19, s8, s22
	s_cselect_b32 s18, s9, s15
	s_add_i32 s10, 0, 0x14000
	v_add_u32_e32 v168, s27, v157
	v_add_u32_e32 v184, s10, v157
	ds_read_b128 v[152:155], v168
	ds_read_b128 v[160:163], v168 offset:1024
	ds_read_b128 v[164:167], v168 offset:2048
	ds_read_b128 v[168:171], v168 offset:3072
	ds_read_b128 v[172:175], v184
	ds_read_b128 v[176:179], v184 offset:1024
	ds_read_b128 v[180:183], v184 offset:2048
	ds_read_b128 v[184:187], v184 offset:3072
	v_lshl_add_u64 v[200:201], s[16:17], 0, v[148:149]
	s_add_i32 m0, s57, 0xc000
	ds_read_b128 v[188:191], v159
	ds_read_b128 v[192:195], v159 offset:1024
	ds_read_b128 v[196:199], v159 offset:2048
	ds_read_b128 v[216:219], v159 offset:3072
	ds_read_b128 v[220:223], v159 offset:4096
	ds_read_b128 v[224:227], v159 offset:5120
	ds_read_b128 v[228:231], v159 offset:6144
	ds_read_b128 v[232:235], v159 offset:7168
	global_load_lds_dwordx4 v[200:201], off
	v_lshl_add_u64 v[200:201], s[16:17], 0, v[150:151]
	s_add_i32 m0, s57, 0xe000
	s_nop 0
	global_load_lds_dwordx4 v[200:201], off
	s_waitcnt vmcnt(8)
	s_waitcnt lgkmcnt(0)
	s_barrier
	s_setprio 1
	v_mfma_f32_16x16x32_bf16 v[126:129], v[152:155], v[188:191], v[126:129]
	v_mfma_f32_16x16x32_bf16 v[122:125], v[164:167], v[188:191], v[122:125]
	v_mfma_f32_16x16x32_bf16 v[110:113], v[152:155], v[196:199], v[110:113]
	v_mfma_f32_16x16x32_bf16 v[106:109], v[164:167], v[196:199], v[106:109]
	v_mfma_f32_16x16x32_bf16 v[94:97], v[152:155], v[220:223], v[94:97]
	v_mfma_f32_16x16x32_bf16 v[90:93], v[164:167], v[220:223], v[90:93]
	v_mfma_f32_16x16x32_bf16 v[78:81], v[152:155], v[228:231], v[78:81]
	v_mfma_f32_16x16x32_bf16 v[74:77], v[164:167], v[228:231], v[74:77]
	v_mfma_f32_16x16x32_bf16 v[126:129], v[160:163], v[192:195], v[126:129]
	v_mfma_f32_16x16x32_bf16 v[122:125], v[168:171], v[192:195], v[122:125]
	v_mfma_f32_16x16x32_bf16 v[110:113], v[160:163], v[216:219], v[110:113]
	v_mfma_f32_16x16x32_bf16 v[106:109], v[168:171], v[216:219], v[106:109]
	v_mfma_f32_16x16x32_bf16 v[94:97], v[160:163], v[224:227], v[94:97]
	v_mfma_f32_16x16x32_bf16 v[90:93], v[168:171], v[224:227], v[90:93]
	v_mfma_f32_16x16x32_bf16 v[78:81], v[160:163], v[232:235], v[78:81]
	v_mfma_f32_16x16x32_bf16 v[74:77], v[168:171], v[232:235], v[74:77]
	v_mfma_f32_16x16x32_bf16 v[118:121], v[172:175], v[188:191], v[118:121]
	v_mfma_f32_16x16x32_bf16 v[114:117], v[180:183], v[188:191], v[114:117]
	v_mfma_f32_16x16x32_bf16 v[102:105], v[172:175], v[196:199], v[102:105]
	v_mfma_f32_16x16x32_bf16 v[98:101], v[180:183], v[196:199], v[98:101]
	v_mfma_f32_16x16x32_bf16 v[86:89], v[172:175], v[220:223], v[86:89]
	v_mfma_f32_16x16x32_bf16 v[82:85], v[180:183], v[220:223], v[82:85]
	v_mfma_f32_16x16x32_bf16 v[70:73], v[172:175], v[228:231], v[70:73]
	v_mfma_f32_16x16x32_bf16 v[66:69], v[180:183], v[228:231], v[66:69]
	v_mfma_f32_16x16x32_bf16 v[118:121], v[176:179], v[192:195], v[118:121]
	v_mfma_f32_16x16x32_bf16 v[114:117], v[184:187], v[192:195], v[114:117]
	v_mfma_f32_16x16x32_bf16 v[102:105], v[176:179], v[216:219], v[102:105]
	v_mfma_f32_16x16x32_bf16 v[98:101], v[184:187], v[216:219], v[98:101]
	v_mfma_f32_16x16x32_bf16 v[86:89], v[176:179], v[224:227], v[86:89]
	v_mfma_f32_16x16x32_bf16 v[82:85], v[184:187], v[224:227], v[82:85]
	v_mfma_f32_16x16x32_bf16 v[70:73], v[176:179], v[232:235], v[70:73]
	v_mfma_f32_16x16x32_bf16 v[66:69], v[184:187], v[232:235], v[66:69]
	s_setprio 0
	s_barrier
	s_add_i32 s11, s27, s56
	v_lshl_add_u64 v[200:201], s[18:19], 0, v[0:1]
	s_mov_b32 m0, s11
	ds_read_b128 v[188:191], v159 offset:16384
	ds_read_b128 v[192:195], v159 offset:17408
	ds_read_b128 v[196:199], v159 offset:18432
	ds_read_b128 v[216:219], v159 offset:19456
	ds_read_b128 v[220:223], v159 offset:20480
	ds_read_b128 v[224:227], v159 offset:21504
	ds_read_b128 v[228:231], v159 offset:22528
	ds_read_b128 v[232:235], v159 offset:23552
	global_load_lds_dwordx4 v[200:201], off
	s_add_i32 m0, s11, 0x2000
	s_add_u32 s38, s18, 0x80000
	v_lshl_add_u64 v[236:237], s[18:19], 0, v[142:143]
	s_addc_u32 s39, s19, 0
	s_add_i32 s10, s10, s56
	global_load_lds_dwordx4 v[236:237], off
	v_lshl_add_u64 v[238:239], s[38:39], 0, v[0:1]
	s_mov_b32 m0, s10
	v_lshl_add_u64 v[240:241], s[50:51], 0, v[144:145]
	global_load_lds_dwordx4 v[238:239], off
	v_lshl_add_u64 v[238:239], s[38:39], 0, v[142:143]
	s_add_i32 m0, s10, 0x2000
	s_nop 0
	global_load_lds_dwordx4 v[238:239], off
	v_lshl_add_u64 v[238:239], s[50:51], 0, v[146:147]
	s_mov_b32 m0, s57
	s_nop 0
	global_load_lds_dwordx4 v[238:239], off
	s_mov_b32 m0, s58
	s_nop 0
	global_load_lds_dwordx4 v[240:241], off
	s_waitcnt vmcnt(8)
	s_waitcnt lgkmcnt(0)
	s_barrier
; #define PG8_STAGE(bufoff, gbase, voff) do { _Pragma("unroll") for (int _i = 0; _i < 2; ++_i) \
;         __builtin_amdgcn_global_load_lds((const unsigned*)((const char*)(gbase) + (voff)[_i]), (PG8_LAS unsigned*)(lds + (bufoff) + ldsw + _i * 8192), 16, 0, 0); } while (0)
; #define PG8_LDA(dst, b, h) do { _Pragma("unroll") for (int m = 0; m < 4; ++m) _Pragma("unroll") for (int k = 0; k < 2; ++k) dst[m][k] = *(const PG8_LAS bf16x8*)(lds + PG8_SA(b, h) + aoff + m * 2048 + k * 1024); } while (0)
; #define PG8_LDB(dst, b, h) do { _Pragma("unroll") for (int n = 0; n < 2; ++n) _Pragma("unroll") for (int k = 0; k < 2; ++k) dst[n][k] = *(const PG8_LAS bf16x8*)(lds + PG8_SB(b, h) + boff + n * 2048 + k * 1024); } while (0)
; #define PG8_MMA(ai, bj, At, Bt) do { __builtin_amdgcn_s_setprio(1); _Pragma("unroll") for (int m = 0; m < 4; ++m) _Pragma("unroll") for (int n = 0; n < 2; ++n) _Pragma("unroll") for (int k = 0; k < 2; ++k) \
;         acc[ai][bj][m][n] = __builtin_amdgcn_mfma_f32_16x16x32_bf16(Bt[n][k], At[m][k], acc[ai][bj][m][n], 0, 0, 0); __builtin_amdgcn_s_setprio(0); } while (0)
; #define PG8_WAIT_V(n) asm volatile("s_waitcnt vmcnt(" #n ")" ::: "memory")
; #define PG8_WAIT_L(n) asm volatile("s_waitcnt lgkmcnt(" #n ")" ::: "memory")
; #define PG8_BAR __builtin_amdgcn_s_barrier()
; #define PG8_SCHED __builtin_amdgcn_sched_barrier(0)
; template <class Epi, class Sched, bool ALIGN_EPI = false, bool SP2 = false>
; __device__ __forceinline__ void gemm_phase(PG8_LAS unsigned char* lds, const Gemm g, const Sched& S, const Epi& E) {
;     ...
;             PG8_WAIT_V(8); PG8_WAIT_L(0); PG8_BAR; PG8_MMA(1, 0, At, B0); PG8_MMA(1, 1, At, B1); PG8_BAR; PG8_SCHED;
;             PG8_LDB(B0, 1, 0); PG8_LDB(B1, 1, 1); PG8_SCHED; PG8_LDA(At, 1, 0); PG8_STAGE(PG8_SA(0, 1), a2 + hstep, voffA);
;             PG8_WAIT_V(8); PG8_WAIT_L(0); PG8_BAR; PG8_MMA(0, 0, At, B0); PG8_MMA(0, 1, At, B1); PG8_BAR; PG8_SCHED;
	s_setprio 1
	v_mfma_f32_16x16x32_bf16 v[62:65], v[152:155], v[188:191], v[62:65]
	v_mfma_f32_16x16x32_bf16 v[58:61], v[164:167], v[188:191], v[58:61]
	v_mfma_f32_16x16x32_bf16 v[50:53], v[152:155], v[196:199], v[50:53]
	v_mfma_f32_16x16x32_bf16 v[42:45], v[164:167], v[196:199], v[42:45]
	v_mfma_f32_16x16x32_bf16 v[34:37], v[152:155], v[220:223], v[34:37]
	v_mfma_f32_16x16x32_bf16 v[26:29], v[164:167], v[220:223], v[26:29]
	v_mfma_f32_16x16x32_bf16 v[18:21], v[152:155], v[228:231], v[18:21]
	v_mfma_f32_16x16x32_bf16 v[10:13], v[164:167], v[228:231], v[10:13]
	v_mfma_f32_16x16x32_bf16 v[62:65], v[160:163], v[192:195], v[62:65]
	v_mfma_f32_16x16x32_bf16 v[58:61], v[168:171], v[192:195], v[58:61]
	v_mfma_f32_16x16x32_bf16 v[50:53], v[160:163], v[216:219], v[50:53]
	v_mfma_f32_16x16x32_bf16 v[42:45], v[168:171], v[216:219], v[42:45]
	v_mfma_f32_16x16x32_bf16 v[34:37], v[160:163], v[224:227], v[34:37]
	v_mfma_f32_16x16x32_bf16 v[26:29], v[168:171], v[224:227], v[26:29]
	v_mfma_f32_16x16x32_bf16 v[18:21], v[160:163], v[232:235], v[18:21]
	v_mfma_f32_16x16x32_bf16 v[10:13], v[168:171], v[232:235], v[10:13]
	v_mfma_f32_16x16x32_bf16 v[54:57], v[172:175], v[188:191], v[54:57]
	v_mfma_f32_16x16x32_bf16 v[46:49], v[180:183], v[188:191], v[46:49]
	v_mfma_f32_16x16x32_bf16 v[38:41], v[172:175], v[196:199], v[38:41]
	v_mfma_f32_16x16x32_bf16 v[30:33], v[180:183], v[196:199], v[30:33]
	v_mfma_f32_16x16x32_bf16 v[22:25], v[172:175], v[220:223], v[22:25]
	v_mfma_f32_16x16x32_bf16 v[14:17], v[180:183], v[220:223], v[14:17]
	v_mfma_f32_16x16x32_bf16 v[6:9], v[172:175], v[228:231], v[6:9]
	v_mfma_f32_16x16x32_bf16 v[2:5], v[180:183], v[228:231], v[2:5]
	v_mfma_f32_16x16x32_bf16 v[54:57], v[176:179], v[192:195], v[54:57]
	v_mfma_f32_16x16x32_bf16 v[46:49], v[184:187], v[192:195], v[46:49]
	v_mfma_f32_16x16x32_bf16 v[38:41], v[176:179], v[216:219], v[38:41]
	v_mfma_f32_16x16x32_bf16 v[30:33], v[184:187], v[216:219], v[30:33]
	v_mfma_f32_16x16x32_bf16 v[22:25], v[176:179], v[224:227], v[22:25]
	v_mfma_f32_16x16x32_bf16 v[14:17], v[184:187], v[224:227], v[14:17]
	v_mfma_f32_16x16x32_bf16 v[6:9], v[176:179], v[232:235], v[6:9]
	v_mfma_f32_16x16x32_bf16 v[2:5], v[184:187], v[232:235], v[2:5]
	s_setprio 0
	s_barrier
	s_add_i32 s10, 0, 0x18000
	s_add_i32 s11, 0, 0x1c000
	v_add_u32_e32 v168, s10, v157
	v_add_u32_e32 v184, s11, v157
	ds_read_b128 v[152:155], v168
	ds_read_b128 v[160:163], v168 offset:1024
	ds_read_b128 v[164:167], v168 offset:2048
	ds_read_b128 v[168:171], v168 offset:3072
	ds_read_b128 v[172:175], v184
	ds_read_b128 v[176:179], v184 offset:1024
	ds_read_b128 v[180:183], v184 offset:2048
	ds_read_b128 v[184:187], v184 offset:3072
	s_add_u32 s38, s50, 0x80000
	s_addc_u32 s39, s51, 0
	s_mov_b32 m0, s59
	v_lshl_add_u64 v[242:243], s[38:39], 0, v[146:147]
	ds_read_b128 v[188:191], v159 offset:32768
	ds_read_b128 v[192:195], v159 offset:33792
	ds_read_b128 v[196:199], v159 offset:34816
	ds_read_b128 v[216:219], v159 offset:35840
	ds_read_b128 v[220:223], v159 offset:36864
	ds_read_b128 v[224:227], v159 offset:37888
	ds_read_b128 v[228:231], v159 offset:38912
	ds_read_b128 v[232:235], v159 offset:39936
	global_load_lds_dwordx4 v[242:243], off
	v_lshl_add_u64 v[242:243], s[38:39], 0, v[144:145]
	s_mov_b32 m0, s60
	s_nop 0
	global_load_lds_dwordx4 v[242:243], off
	s_waitcnt vmcnt(8)
	s_waitcnt lgkmcnt(0)
	s_barrier
	s_setprio 1
	v_mfma_f32_16x16x32_bf16 v[126:129], v[152:155], v[188:191], v[126:129]
	v_mfma_f32_16x16x32_bf16 v[122:125], v[164:167], v[188:191], v[122:125]
	v_mfma_f32_16x16x32_bf16 v[110:113], v[152:155], v[196:199], v[110:113]
	v_mfma_f32_16x16x32_bf16 v[106:109], v[164:167], v[196:199], v[106:109]
	v_mfma_f32_16x16x32_bf16 v[94:97], v[152:155], v[220:223], v[94:97]
	v_mfma_f32_16x16x32_bf16 v[90:93], v[164:167], v[220:223], v[90:93]
	v_mfma_f32_16x16x32_bf16 v[78:81], v[152:155], v[228:231], v[78:81]
	v_mfma_f32_16x16x32_bf16 v[74:77], v[164:167], v[228:231], v[74:77]
	v_mfma_f32_16x16x32_bf16 v[126:129], v[160:163], v[192:195], v[126:129]
	v_mfma_f32_16x16x32_bf16 v[122:125], v[168:171], v[192:195], v[122:125]
	v_mfma_f32_16x16x32_bf16 v[110:113], v[160:163], v[216:219], v[110:113]
	v_mfma_f32_16x16x32_bf16 v[106:109], v[168:171], v[216:219], v[106:109]
	v_mfma_f32_16x16x32_bf16 v[94:97], v[160:163], v[224:227], v[94:97]
	v_mfma_f32_16x16x32_bf16 v[90:93], v[168:171], v[224:227], v[90:93]
	v_mfma_f32_16x16x32_bf16 v[78:81], v[160:163], v[232:235], v[78:81]
	v_mfma_f32_16x16x32_bf16 v[74:77], v[168:171], v[232:235], v[74:77]
	v_mfma_f32_16x16x32_bf16 v[118:121], v[172:175], v[188:191], v[118:121]
	v_mfma_f32_16x16x32_bf16 v[114:117], v[180:183], v[188:191], v[114:117]
	v_mfma_f32_16x16x32_bf16 v[102:105], v[172:175], v[196:199], v[102:105]
	v_mfma_f32_16x16x32_bf16 v[98:101], v[180:183], v[196:199], v[98:101]
	v_mfma_f32_16x16x32_bf16 v[86:89], v[172:175], v[220:223], v[86:89]
	v_mfma_f32_16x16x32_bf16 v[82:85], v[180:183], v[220:223], v[82:85]
	v_mfma_f32_16x16x32_bf16 v[70:73], v[172:175], v[228:231], v[70:73]
	v_mfma_f32_16x16x32_bf16 v[66:69], v[180:183], v[228:231], v[66:69]
	v_mfma_f32_16x16x32_bf16 v[118:121], v[176:179], v[192:195], v[118:121]
	v_mfma_f32_16x16x32_bf16 v[114:117], v[184:187], v[192:195], v[114:117]
	v_mfma_f32_16x16x32_bf16 v[102:105], v[176:179], v[216:219], v[102:105]
	v_mfma_f32_16x16x32_bf16 v[98:101], v[184:187], v[216:219], v[98:101]
	v_mfma_f32_16x16x32_bf16 v[86:89], v[176:179], v[224:227], v[86:89]
	v_mfma_f32_16x16x32_bf16 v[82:85], v[184:187], v[224:227], v[82:85]
	v_mfma_f32_16x16x32_bf16 v[70:73], v[176:179], v[232:235], v[70:73]
	v_mfma_f32_16x16x32_bf16 v[66:69], v[184:187], v[232:235], v[66:69]
	s_setprio 0
	s_barrier
; #define PG8_STAGE(bufoff, gbase, voff) do { _Pragma("unroll") for (int _i = 0; _i < 2; ++_i) \
;         __builtin_amdgcn_global_load_lds((const unsigned*)((const char*)(gbase) + (voff)[_i]), (PG8_LAS unsigned*)(lds + (bufoff) + ldsw + _i * 8192), 16, 0, 0); } while (0)
; #define PG8_LDA(dst, b, h) do { _Pragma("unroll") for (int m = 0; m < 4; ++m) _Pragma("unroll") for (int k = 0; k < 2; ++k) dst[m][k] = *(const PG8_LAS bf16x8*)(lds + PG8_SA(b, h) + aoff + m * 2048 + k * 1024); } while (0)
; #define PG8_MMA(ai, bj, At, Bt) do { __builtin_amdgcn_s_setprio(1); _Pragma("unroll") for (int m = 0; m < 4; ++m) _Pragma("unroll") for (int n = 0; n < 2; ++n) _Pragma("unroll") for (int k = 0; k < 2; ++k) \
;         acc[ai][bj][m][n] = __builtin_amdgcn_mfma_f32_16x16x32_bf16(Bt[n][k], At[m][k], acc[ai][bj][m][n], 0, 0, 0); __builtin_amdgcn_s_setprio(0); } while (0)
; #define PG8_WAIT_V(n) asm volatile("s_waitcnt vmcnt(" #n ")" ::: "memory")
; #define PG8_WAIT_L(n) asm volatile("s_waitcnt lgkmcnt(" #n ")" ::: "memory")
; #define PG8_BAR __builtin_amdgcn_s_barrier()
; #define PG8_SCHED __builtin_amdgcn_sched_barrier(0)
; template <class Epi, class Sched, bool ALIGN_EPI = false, bool SP2 = false>
; __device__ __forceinline__ void gemm_phase(PG8_LAS unsigned char* lds, const Gemm g, const Sched& S, const Epi& E) {
;     ...
;             PG8_LDA(At, 1, 1); PG8_STAGE(PG8_SB(1, 0), b3, voffB); PG8_STAGE(PG8_SB(1, 1), b3 + hstep, voffB); PG8_STAGE(PG8_SA(1, 0), a3, voffA);
;             PG8_WAIT_V(8); PG8_WAIT_L(0); PG8_BAR; PG8_MMA(1, 0, At, B0); PG8_MMA(1, 1, At, B1); PG8_BAR; PG8_SCHED;
;     ...
;         if constexpr (ALIGN_EPI) { if (wr == 0) PG8_BAR; }
	s_add_i32 s10, s10, s56
	v_lshl_add_u64 v[200:201], v[200:201], 0, s[30:31]
	s_mov_b32 m0, s10
	ds_read_b128 v[188:191], v159 offset:49152
	ds_read_b128 v[192:195], v159 offset:50176
	ds_read_b128 v[196:199], v159 offset:51200
	ds_read_b128 v[216:219], v159 offset:52224
	ds_read_b128 v[220:223], v159 offset:53248
	ds_read_b128 v[224:227], v159 offset:54272
	ds_read_b128 v[228:231], v159 offset:55296
	ds_read_b128 v[232:235], v159 offset:56320
	global_load_lds_dwordx4 v[200:201], off
	s_add_i32 m0, s10, 0x2000
	s_add_u32 s18, s18, 0x80080
	v_lshl_add_u64 v[200:201], v[236:237], 0, s[30:31]
	s_addc_u32 s19, s19, 0
	s_add_i32 s10, s11, s56
	global_load_lds_dwordx4 v[200:201], off
	v_lshl_add_u64 v[200:201], s[18:19], 0, v[0:1]
	s_mov_b32 m0, s10
	s_nop 0
	global_load_lds_dwordx4 v[200:201], off
	v_lshl_add_u64 v[200:201], s[18:19], 0, v[142:143]
	s_add_i32 m0, s10, 0x2000
	s_nop 0
	global_load_lds_dwordx4 v[200:201], off
	v_lshl_add_u64 v[200:201], v[238:239], 0, s[30:31]
	s_mov_b32 m0, s61
	s_nop 0
	global_load_lds_dwordx4 v[200:201], off
	v_lshl_add_u64 v[200:201], v[240:241], 0, s[30:31]
	s_mov_b32 m0, s62
	s_nop 0
	global_load_lds_dwordx4 v[200:201], off
	s_waitcnt vmcnt(8)
	s_waitcnt lgkmcnt(0)
	s_barrier
	s_setprio 1
	v_mfma_f32_16x16x32_bf16 v[62:65], v[152:155], v[188:191], v[62:65]
	v_mfma_f32_16x16x32_bf16 v[58:61], v[164:167], v[188:191], v[58:61]
	v_mfma_f32_16x16x32_bf16 v[50:53], v[152:155], v[196:199], v[50:53]
	v_mfma_f32_16x16x32_bf16 v[42:45], v[164:167], v[196:199], v[42:45]
	v_mfma_f32_16x16x32_bf16 v[34:37], v[152:155], v[220:223], v[34:37]
	v_mfma_f32_16x16x32_bf16 v[26:29], v[164:167], v[220:223], v[26:29]
	v_mfma_f32_16x16x32_bf16 v[18:21], v[152:155], v[228:231], v[18:21]
	v_mfma_f32_16x16x32_bf16 v[10:13], v[164:167], v[228:231], v[10:13]
	v_mfma_f32_16x16x32_bf16 v[62:65], v[160:163], v[192:195], v[62:65]
	v_mfma_f32_16x16x32_bf16 v[58:61], v[168:171], v[192:195], v[58:61]
	v_mfma_f32_16x16x32_bf16 v[50:53], v[160:163], v[216:219], v[50:53]
	v_mfma_f32_16x16x32_bf16 v[42:45], v[168:171], v[216:219], v[42:45]
	v_mfma_f32_16x16x32_bf16 v[34:37], v[160:163], v[224:227], v[34:37]
	v_mfma_f32_16x16x32_bf16 v[26:29], v[168:171], v[224:227], v[26:29]
	v_mfma_f32_16x16x32_bf16 v[18:21], v[160:163], v[232:235], v[18:21]
	v_mfma_f32_16x16x32_bf16 v[10:13], v[168:171], v[232:235], v[10:13]
	v_mfma_f32_16x16x32_bf16 v[54:57], v[172:175], v[188:191], v[54:57]
	v_mfma_f32_16x16x32_bf16 v[46:49], v[180:183], v[188:191], v[46:49]
	v_mfma_f32_16x16x32_bf16 v[38:41], v[172:175], v[196:199], v[38:41]
	v_mfma_f32_16x16x32_bf16 v[30:33], v[180:183], v[196:199], v[30:33]
	v_mfma_f32_16x16x32_bf16 v[22:25], v[172:175], v[220:223], v[22:25]
	v_mfma_f32_16x16x32_bf16 v[14:17], v[180:183], v[220:223], v[14:17]
	v_mfma_f32_16x16x32_bf16 v[6:9], v[172:175], v[228:231], v[6:9]
	v_mfma_f32_16x16x32_bf16 v[2:5], v[180:183], v[228:231], v[2:5]
	v_mfma_f32_16x16x32_bf16 v[54:57], v[176:179], v[192:195], v[54:57]
	v_mfma_f32_16x16x32_bf16 v[46:49], v[184:187], v[192:195], v[46:49]
	v_mfma_f32_16x16x32_bf16 v[38:41], v[176:179], v[216:219], v[38:41]
	v_mfma_f32_16x16x32_bf16 v[30:33], v[184:187], v[216:219], v[30:33]
	v_mfma_f32_16x16x32_bf16 v[22:25], v[176:179], v[224:227], v[22:25]
	v_mfma_f32_16x16x32_bf16 v[14:17], v[184:187], v[224:227], v[14:17]
	v_mfma_f32_16x16x32_bf16 v[6:9], v[176:179], v[232:235], v[6:9]
	v_mfma_f32_16x16x32_bf16 v[2:5], v[184:187], v[232:235], v[2:5]
	s_setprio 0
	s_barrier
	s_add_i32 s23, s23, 2
	s_add_u32 s16, s16, 0x100
	s_addc_u32 s17, s17, 0
	s_add_u32 s15, s15, 0x100
	s_addc_u32 s22, s22, 0
	s_cmp_gt_u32 s23, 29
	s_cbranch_scc0 .LBB0_265
	s_and_b64 vcc, exec, s[24:25]
	s_cbranch_vccz .LBB0_268
	s_barrier

; #define PG8_STAGE(bufoff, gbase, voff) do { _Pragma("unroll") for (int _i = 0; _i < 2; ++_i) \
;         __builtin_amdgcn_global_load_lds((const unsigned*)((const char*)(gbase) + (voff)[_i]), (PG8_LAS unsigned*)(lds + (bufoff) + ldsw + _i * 8192), 16, 0, 0); } while (0)
; #define PG8_LDA(dst, b, h) do { _Pragma("unroll") for (int m = 0; m < 4; ++m) _Pragma("unroll") for (int k = 0; k < 2; ++k) dst[m][k] = *(const PG8_LAS bf16x8*)(lds + PG8_SA(b, h) + aoff + m * 2048 + k * 1024); } while (0)
; #define PG8_LDB(dst, b, h) do { _Pragma("unroll") for (int n = 0; n < 2; ++n) _Pragma("unroll") for (int k = 0; k < 2; ++k) dst[n][k] = *(const PG8_LAS bf16x8*)(lds + PG8_SB(b, h) + boff + n * 2048 + k * 1024); } while (0)
; #define PG8_MMA(ai, bj, At, Bt) do { __builtin_amdgcn_s_setprio(1); _Pragma("unroll") for (int m = 0; m < 4; ++m) _Pragma("unroll") for (int n = 0; n < 2; ++n) _Pragma("unroll") for (int k = 0; k < 2; ++k) \
;         acc[ai][bj][m][n] = __builtin_amdgcn_mfma_f32_16x16x32_bf16(Bt[n][k], At[m][k], acc[ai][bj][m][n], 0, 0, 0); __builtin_amdgcn_s_setprio(0); } while (0)
; #define PG8_WAIT_V(n) asm volatile("s_waitcnt vmcnt(" #n ")" ::: "memory")
; #define PG8_WAIT_L(n) asm volatile("s_waitcnt lgkmcnt(" #n ")" ::: "memory")
; #define PG8_BAR __builtin_amdgcn_s_barrier()
; #define PG8_SCHED __builtin_amdgcn_sched_barrier(0)
; template <class Epi, class Sched, bool ALIGN_EPI = false, bool SP2 = false>
; __device__ __forceinline__ void gemm_phase(PG8_LAS unsigned char* lds, const Gemm g, const Sched& S, const Epi& E) {
;     ...
;             PG8_LDB(B0, 0, 0); PG8_LDB(B1, 0, 1); PG8_SCHED; PG8_LDA(At, 0, 0); PG8_STAGE(PG8_SA(1, 1), a1 + hstep, voffA);
;             PG8_WAIT_V(8); PG8_WAIT_L(0); PG8_BAR; PG8_MMA(0, 0, At, B0); PG8_MMA(0, 1, At, B1); PG8_BAR; PG8_SCHED;
;             PG8_LDA(At, 0, 1); PG8_STAGE(PG8_SB(0, 0), b2, voffB); PG8_STAGE(PG8_SB(0, 1), b2 + hstep, voffB); PG8_STAGE(PG8_SA(0, 0), a2, voffA);
.LBB0_601:
	s_add_u32 s18, s16, 0x100
	s_addc_u32 s19, s17, 0
	s_add_i32 s10, 0, 0x10000
	s_cmp_eq_u32 s22, 28
	s_cselect_b32 s27, s5, s19
	s_cselect_b32 s26, s7, s18
	s_cselect_b32 s25, s8, s15
	s_cselect_b32 s24, s9, s14
	s_add_i32 s12, 0, 0x14000
	v_add_u32_e32 v160, s10, v187
	v_add_u32_e32 v176, s12, v187
	ds_read_b128 v[148:151], v160
	ds_read_b128 v[152:155], v160 offset:1024
	ds_read_b128 v[156:159], v160 offset:2048
	ds_read_b128 v[160:163], v160 offset:3072
	ds_read_b128 v[164:167], v176
	ds_read_b128 v[168:171], v176 offset:1024
	ds_read_b128 v[172:175], v176 offset:2048
	ds_read_b128 v[176:179], v176 offset:3072
	v_lshl_add_u64 v[184:185], s[16:17], 0, v[144:145]
	s_add_i32 m0, s61, 0xc000
	ds_read_b128 v[180:183], v189
	ds_read_b128 v[190:193], v189 offset:1024
	ds_read_b128 v[194:197], v189 offset:2048
	ds_read_b128 v[198:201], v189 offset:3072
	ds_read_b128 v[216:219], v189 offset:4096
	ds_read_b128 v[220:223], v189 offset:5120
	ds_read_b128 v[224:227], v189 offset:6144
	ds_read_b128 v[228:231], v189 offset:7168
	global_load_lds_dwordx4 v[184:185], off
	v_lshl_add_u64 v[184:185], s[16:17], 0, v[146:147]
	s_add_i32 m0, s61, 0xe000
	s_nop 0
	global_load_lds_dwordx4 v[184:185], off
	s_waitcnt vmcnt(8)
	s_waitcnt lgkmcnt(0)
	s_barrier
	s_setprio 1
	v_mfma_f32_16x16x32_bf16 v[126:129], v[148:151], v[180:183], v[126:129]
	v_mfma_f32_16x16x32_bf16 v[122:125], v[156:159], v[180:183], v[122:125]
	v_mfma_f32_16x16x32_bf16 v[110:113], v[148:151], v[194:197], v[110:113]
	v_mfma_f32_16x16x32_bf16 v[106:109], v[156:159], v[194:197], v[106:109]
	v_mfma_f32_16x16x32_bf16 v[94:97], v[148:151], v[216:219], v[94:97]
	v_mfma_f32_16x16x32_bf16 v[90:93], v[156:159], v[216:219], v[90:93]
	v_mfma_f32_16x16x32_bf16 v[78:81], v[148:151], v[224:227], v[78:81]
	v_mfma_f32_16x16x32_bf16 v[74:77], v[156:159], v[224:227], v[74:77]
	v_mfma_f32_16x16x32_bf16 v[126:129], v[152:155], v[190:193], v[126:129]
	v_mfma_f32_16x16x32_bf16 v[122:125], v[160:163], v[190:193], v[122:125]
	v_mfma_f32_16x16x32_bf16 v[110:113], v[152:155], v[198:201], v[110:113]
	v_mfma_f32_16x16x32_bf16 v[106:109], v[160:163], v[198:201], v[106:109]
	v_mfma_f32_16x16x32_bf16 v[94:97], v[152:155], v[220:223], v[94:97]
	v_mfma_f32_16x16x32_bf16 v[90:93], v[160:163], v[220:223], v[90:93]
	v_mfma_f32_16x16x32_bf16 v[78:81], v[152:155], v[228:231], v[78:81]
	v_mfma_f32_16x16x32_bf16 v[74:77], v[160:163], v[228:231], v[74:77]
	v_mfma_f32_16x16x32_bf16 v[118:121], v[164:167], v[180:183], v[118:121]
	v_mfma_f32_16x16x32_bf16 v[114:117], v[172:175], v[180:183], v[114:117]
	v_mfma_f32_16x16x32_bf16 v[102:105], v[164:167], v[194:197], v[102:105]
	v_mfma_f32_16x16x32_bf16 v[98:101], v[172:175], v[194:197], v[98:101]
	v_mfma_f32_16x16x32_bf16 v[86:89], v[164:167], v[216:219], v[86:89]
	v_mfma_f32_16x16x32_bf16 v[82:85], v[172:175], v[216:219], v[82:85]
	v_mfma_f32_16x16x32_bf16 v[70:73], v[164:167], v[224:227], v[70:73]
	v_mfma_f32_16x16x32_bf16 v[66:69], v[172:175], v[224:227], v[66:69]
	v_mfma_f32_16x16x32_bf16 v[118:121], v[168:171], v[190:193], v[118:121]
	v_mfma_f32_16x16x32_bf16 v[114:117], v[176:179], v[190:193], v[114:117]
	v_mfma_f32_16x16x32_bf16 v[102:105], v[168:171], v[198:201], v[102:105]
	v_mfma_f32_16x16x32_bf16 v[98:101], v[176:179], v[198:201], v[98:101]
	v_mfma_f32_16x16x32_bf16 v[86:89], v[168:171], v[220:223], v[86:89]
	v_mfma_f32_16x16x32_bf16 v[82:85], v[176:179], v[220:223], v[82:85]
	v_mfma_f32_16x16x32_bf16 v[70:73], v[168:171], v[228:231], v[70:73]
	v_mfma_f32_16x16x32_bf16 v[66:69], v[176:179], v[228:231], v[66:69]
	s_setprio 0
	s_barrier
	s_add_i32 s10, s10, s60
	v_lshl_add_u64 v[184:185], s[24:25], 0, v[0:1]
	s_mov_b32 m0, s10
	ds_read_b128 v[180:183], v189 offset:16384
	ds_read_b128 v[190:193], v189 offset:17408
	ds_read_b128 v[194:197], v189 offset:18432
	ds_read_b128 v[198:201], v189 offset:19456
	ds_read_b128 v[216:219], v189 offset:20480
	ds_read_b128 v[220:223], v189 offset:21504
	ds_read_b128 v[224:227], v189 offset:22528
	ds_read_b128 v[228:231], v189 offset:23552
	global_load_lds_dwordx4 v[184:185], off
	s_add_i32 m0, s10, 0x2000
	s_add_u32 s10, s24, 0x80000
	v_lshl_add_u64 v[232:233], s[24:25], 0, v[142:143]
	s_addc_u32 s11, s25, 0
	s_add_i32 s12, s12, s60
	global_load_lds_dwordx4 v[232:233], off
	v_lshl_add_u64 v[234:235], s[10:11], 0, v[0:1]
	s_mov_b32 m0, s12
	v_lshl_add_u64 v[236:237], s[26:27], 0, v[142:143]
	global_load_lds_dwordx4 v[234:235], off
	v_lshl_add_u64 v[234:235], s[10:11], 0, v[142:143]
	s_add_i32 m0, s12, 0x2000
	s_nop 0
	global_load_lds_dwordx4 v[234:235], off
	v_lshl_add_u64 v[234:235], s[26:27], 0, v[0:1]
	s_mov_b32 m0, s61
	s_nop 0
	global_load_lds_dwordx4 v[234:235], off
	s_mov_b32 m0, s62
	s_nop 0
	global_load_lds_dwordx4 v[236:237], off
	s_waitcnt vmcnt(8)
	s_waitcnt lgkmcnt(0)
	s_barrier
; #define PG8_STAGE(bufoff, gbase, voff) do { _Pragma("unroll") for (int _i = 0; _i < 2; ++_i) \
;         __builtin_amdgcn_global_load_lds((const unsigned*)((const char*)(gbase) + (voff)[_i]), (PG8_LAS unsigned*)(lds + (bufoff) + ldsw + _i * 8192), 16, 0, 0); } while (0)
; #define PG8_LDA(dst, b, h) do { _Pragma("unroll") for (int m = 0; m < 4; ++m) _Pragma("unroll") for (int k = 0; k < 2; ++k) dst[m][k] = *(const PG8_LAS bf16x8*)(lds + PG8_SA(b, h) + aoff + m * 2048 + k * 1024); } while (0)
; #define PG8_LDB(dst, b, h) do { _Pragma("unroll") for (int n = 0; n < 2; ++n) _Pragma("unroll") for (int k = 0; k < 2; ++k) dst[n][k] = *(const PG8_LAS bf16x8*)(lds + PG8_SB(b, h) + boff + n * 2048 + k * 1024); } while (0)
; #define PG8_MMA(ai, bj, At, Bt) do { __builtin_amdgcn_s_setprio(1); _Pragma("unroll") for (int m = 0; m < 4; ++m) _Pragma("unroll") for (int n = 0; n < 2; ++n) _Pragma("unroll") for (int k = 0; k < 2; ++k) \
;         acc[ai][bj][m][n] = __builtin_amdgcn_mfma_f32_16x16x32_bf16(Bt[n][k], At[m][k], acc[ai][bj][m][n], 0, 0, 0); __builtin_amdgcn_s_setprio(0); } while (0)
; #define PG8_WAIT_V(n) asm volatile("s_waitcnt vmcnt(" #n ")" ::: "memory")
; #define PG8_WAIT_L(n) asm volatile("s_waitcnt lgkmcnt(" #n ")" ::: "memory")
; #define PG8_BAR __builtin_amdgcn_s_barrier()
; #define PG8_SCHED __builtin_amdgcn_sched_barrier(0)
; template <class Epi, class Sched, bool ALIGN_EPI = false, bool SP2 = false>
; __device__ __forceinline__ void gemm_phase(PG8_LAS unsigned char* lds, const Gemm g, const Sched& S, const Epi& E) {
;     ...
;             PG8_WAIT_V(8); PG8_WAIT_L(0); PG8_BAR; PG8_MMA(1, 0, At, B0); PG8_MMA(1, 1, At, B1); PG8_BAR; PG8_SCHED;
;             PG8_LDB(B0, 1, 0); PG8_LDB(B1, 1, 1); PG8_SCHED; PG8_LDA(At, 1, 0); PG8_STAGE(PG8_SA(0, 1), a2 + hstep, voffA);
;             PG8_WAIT_V(8); PG8_WAIT_L(0); PG8_BAR; PG8_MMA(0, 0, At, B0); PG8_MMA(0, 1, At, B1); PG8_BAR; PG8_SCHED;
	s_setprio 1
	v_mfma_f32_16x16x32_bf16 v[62:65], v[148:151], v[180:183], v[62:65]
	v_mfma_f32_16x16x32_bf16 v[58:61], v[156:159], v[180:183], v[58:61]
	v_mfma_f32_16x16x32_bf16 v[46:49], v[148:151], v[194:197], v[46:49]
	v_mfma_f32_16x16x32_bf16 v[42:45], v[156:159], v[194:197], v[42:45]
	v_mfma_f32_16x16x32_bf16 v[30:33], v[148:151], v[216:219], v[30:33]
	v_mfma_f32_16x16x32_bf16 v[26:29], v[156:159], v[216:219], v[26:29]
	v_mfma_f32_16x16x32_bf16 v[14:17], v[148:151], v[224:227], v[14:17]
	v_mfma_f32_16x16x32_bf16 v[10:13], v[156:159], v[224:227], v[10:13]
	v_mfma_f32_16x16x32_bf16 v[62:65], v[152:155], v[190:193], v[62:65]
	v_mfma_f32_16x16x32_bf16 v[58:61], v[160:163], v[190:193], v[58:61]
	v_mfma_f32_16x16x32_bf16 v[46:49], v[152:155], v[198:201], v[46:49]
	v_mfma_f32_16x16x32_bf16 v[42:45], v[160:163], v[198:201], v[42:45]
	v_mfma_f32_16x16x32_bf16 v[30:33], v[152:155], v[220:223], v[30:33]
	v_mfma_f32_16x16x32_bf16 v[26:29], v[160:163], v[220:223], v[26:29]
	v_mfma_f32_16x16x32_bf16 v[14:17], v[152:155], v[228:231], v[14:17]
	v_mfma_f32_16x16x32_bf16 v[10:13], v[160:163], v[228:231], v[10:13]
	v_mfma_f32_16x16x32_bf16 v[54:57], v[164:167], v[180:183], v[54:57]
	v_mfma_f32_16x16x32_bf16 v[50:53], v[172:175], v[180:183], v[50:53]
	v_mfma_f32_16x16x32_bf16 v[38:41], v[164:167], v[194:197], v[38:41]
	v_mfma_f32_16x16x32_bf16 v[34:37], v[172:175], v[194:197], v[34:37]
	v_mfma_f32_16x16x32_bf16 v[22:25], v[164:167], v[216:219], v[22:25]
	v_mfma_f32_16x16x32_bf16 v[18:21], v[172:175], v[216:219], v[18:21]
	v_mfma_f32_16x16x32_bf16 v[6:9], v[164:167], v[224:227], v[6:9]
	v_mfma_f32_16x16x32_bf16 v[2:5], v[172:175], v[224:227], v[2:5]
	v_mfma_f32_16x16x32_bf16 v[54:57], v[168:171], v[190:193], v[54:57]
	v_mfma_f32_16x16x32_bf16 v[50:53], v[176:179], v[190:193], v[50:53]
	v_mfma_f32_16x16x32_bf16 v[38:41], v[168:171], v[198:201], v[38:41]
	v_mfma_f32_16x16x32_bf16 v[34:37], v[176:179], v[198:201], v[34:37]
	v_mfma_f32_16x16x32_bf16 v[22:25], v[168:171], v[220:223], v[22:25]
	v_mfma_f32_16x16x32_bf16 v[18:21], v[176:179], v[220:223], v[18:21]
	v_mfma_f32_16x16x32_bf16 v[6:9], v[168:171], v[228:231], v[6:9]
	v_mfma_f32_16x16x32_bf16 v[2:5], v[176:179], v[228:231], v[2:5]
	s_setprio 0
	s_barrier
	s_add_i32 s12, 0, 0x18000
	s_add_i32 s13, 0, 0x1c000
	v_add_u32_e32 v160, s12, v187
	v_add_u32_e32 v176, s13, v187
	ds_read_b128 v[148:151], v160
	ds_read_b128 v[152:155], v160 offset:1024
	ds_read_b128 v[156:159], v160 offset:2048
	ds_read_b128 v[160:163], v160 offset:3072
	ds_read_b128 v[164:167], v176
	ds_read_b128 v[168:171], v176 offset:1024
	ds_read_b128 v[172:175], v176 offset:2048
	ds_read_b128 v[176:179], v176 offset:3072
	s_add_u32 s10, s26, 0x80000
	s_addc_u32 s11, s27, 0
	s_mov_b32 m0, s63
	v_lshl_add_u64 v[238:239], s[10:11], 0, v[0:1]
	ds_read_b128 v[180:183], v189 offset:32768
	ds_read_b128 v[190:193], v189 offset:33792
	ds_read_b128 v[194:197], v189 offset:34816
	ds_read_b128 v[198:201], v189 offset:35840
	ds_read_b128 v[216:219], v189 offset:36864
	ds_read_b128 v[220:223], v189 offset:37888
	ds_read_b128 v[224:227], v189 offset:38912
	ds_read_b128 v[228:231], v189 offset:39936
	global_load_lds_dwordx4 v[238:239], off
	v_lshl_add_u64 v[238:239], s[10:11], 0, v[142:143]
	s_mov_b32 m0, s64
	s_nop 0
	global_load_lds_dwordx4 v[238:239], off
	s_waitcnt vmcnt(8)
	s_waitcnt lgkmcnt(0)
	s_barrier
	s_setprio 1
	v_mfma_f32_16x16x32_bf16 v[126:129], v[148:151], v[180:183], v[126:129]
	v_mfma_f32_16x16x32_bf16 v[122:125], v[156:159], v[180:183], v[122:125]
	v_mfma_f32_16x16x32_bf16 v[110:113], v[148:151], v[194:197], v[110:113]
	v_mfma_f32_16x16x32_bf16 v[106:109], v[156:159], v[194:197], v[106:109]
	v_mfma_f32_16x16x32_bf16 v[94:97], v[148:151], v[216:219], v[94:97]
	v_mfma_f32_16x16x32_bf16 v[90:93], v[156:159], v[216:219], v[90:93]
	v_mfma_f32_16x16x32_bf16 v[78:81], v[148:151], v[224:227], v[78:81]
	v_mfma_f32_16x16x32_bf16 v[74:77], v[156:159], v[224:227], v[74:77]
	v_mfma_f32_16x16x32_bf16 v[126:129], v[152:155], v[190:193], v[126:129]
	v_mfma_f32_16x16x32_bf16 v[122:125], v[160:163], v[190:193], v[122:125]
	v_mfma_f32_16x16x32_bf16 v[110:113], v[152:155], v[198:201], v[110:113]
	v_mfma_f32_16x16x32_bf16 v[106:109], v[160:163], v[198:201], v[106:109]
	v_mfma_f32_16x16x32_bf16 v[94:97], v[152:155], v[220:223], v[94:97]
	v_mfma_f32_16x16x32_bf16 v[90:93], v[160:163], v[220:223], v[90:93]
	v_mfma_f32_16x16x32_bf16 v[78:81], v[152:155], v[228:231], v[78:81]
	v_mfma_f32_16x16x32_bf16 v[74:77], v[160:163], v[228:231], v[74:77]
	v_mfma_f32_16x16x32_bf16 v[118:121], v[164:167], v[180:183], v[118:121]
	v_mfma_f32_16x16x32_bf16 v[114:117], v[172:175], v[180:183], v[114:117]
	v_mfma_f32_16x16x32_bf16 v[102:105], v[164:167], v[194:197], v[102:105]
	v_mfma_f32_16x16x32_bf16 v[98:101], v[172:175], v[194:197], v[98:101]
	v_mfma_f32_16x16x32_bf16 v[86:89], v[164:167], v[216:219], v[86:89]
	v_mfma_f32_16x16x32_bf16 v[82:85], v[172:175], v[216:219], v[82:85]
	v_mfma_f32_16x16x32_bf16 v[70:73], v[164:167], v[224:227], v[70:73]
	v_mfma_f32_16x16x32_bf16 v[66:69], v[172:175], v[224:227], v[66:69]
	v_mfma_f32_16x16x32_bf16 v[118:121], v[168:171], v[190:193], v[118:121]
	v_mfma_f32_16x16x32_bf16 v[114:117], v[176:179], v[190:193], v[114:117]
	v_mfma_f32_16x16x32_bf16 v[102:105], v[168:171], v[198:201], v[102:105]
	v_mfma_f32_16x16x32_bf16 v[98:101], v[176:179], v[198:201], v[98:101]
	v_mfma_f32_16x16x32_bf16 v[86:89], v[168:171], v[220:223], v[86:89]
	v_mfma_f32_16x16x32_bf16 v[82:85], v[176:179], v[220:223], v[82:85]
	v_mfma_f32_16x16x32_bf16 v[70:73], v[168:171], v[228:231], v[70:73]
	v_mfma_f32_16x16x32_bf16 v[66:69], v[176:179], v[228:231], v[66:69]
	s_setprio 0
	s_barrier
; #define PG8_STAGE(bufoff, gbase, voff) do { _Pragma("unroll") for (int _i = 0; _i < 2; ++_i) \
;         __builtin_amdgcn_global_load_lds((const unsigned*)((const char*)(gbase) + (voff)[_i]), (PG8_LAS unsigned*)(lds + (bufoff) + ldsw + _i * 8192), 16, 0, 0); } while (0)
; #define PG8_LDA(dst, b, h) do { _Pragma("unroll") for (int m = 0; m < 4; ++m) _Pragma("unroll") for (int k = 0; k < 2; ++k) dst[m][k] = *(const PG8_LAS bf16x8*)(lds + PG8_SA(b, h) + aoff + m * 2048 + k * 1024); } while (0)
; #define PG8_MMA(ai, bj, At, Bt) do { __builtin_amdgcn_s_setprio(1); _Pragma("unroll") for (int m = 0; m < 4; ++m) _Pragma("unroll") for (int n = 0; n < 2; ++n) _Pragma("unroll") for (int k = 0; k < 2; ++k) \
;         acc[ai][bj][m][n] = __builtin_amdgcn_mfma_f32_16x16x32_bf16(Bt[n][k], At[m][k], acc[ai][bj][m][n], 0, 0, 0); __builtin_amdgcn_s_setprio(0); } while (0)
; #define PG8_WAIT_V(n) asm volatile("s_waitcnt vmcnt(" #n ")" ::: "memory")
; #define PG8_WAIT_L(n) asm volatile("s_waitcnt lgkmcnt(" #n ")" ::: "memory")
; #define PG8_BAR __builtin_amdgcn_s_barrier()
; #define PG8_SCHED __builtin_amdgcn_sched_barrier(0)
; template <class Epi, class Sched, bool ALIGN_EPI = false, bool SP2 = false>
; __device__ __forceinline__ void gemm_phase(PG8_LAS unsigned char* lds, const Gemm g, const Sched& S, const Epi& E) {
;     ...
;         for (int t = 0; t < nt; t += 2) {
;     ...
;             PG8_LDA(At, 1, 1); PG8_STAGE(PG8_SB(1, 0), b3, voffB); PG8_STAGE(PG8_SB(1, 1), b3 + hstep, voffB); PG8_STAGE(PG8_SA(1, 0), a3, voffA);
;             PG8_WAIT_V(8); PG8_WAIT_L(0); PG8_BAR; PG8_MMA(1, 0, At, B0); PG8_MMA(1, 1, At, B1); PG8_BAR; PG8_SCHED;
	s_add_i32 s10, s12, s60
	v_lshl_add_u64 v[184:185], v[184:185], 0, s[30:31]
	s_mov_b32 m0, s10
	ds_read_b128 v[180:183], v189 offset:49152
	ds_read_b128 v[190:193], v189 offset:50176
	ds_read_b128 v[194:197], v189 offset:51200
	ds_read_b128 v[198:201], v189 offset:52224
	ds_read_b128 v[216:219], v189 offset:53248
	ds_read_b128 v[220:223], v189 offset:54272
	ds_read_b128 v[224:227], v189 offset:55296
	ds_read_b128 v[228:231], v189 offset:56320
	global_load_lds_dwordx4 v[184:185], off
	s_add_i32 m0, s10, 0x2000
	s_add_u32 s10, s24, 0x80080
	v_lshl_add_u64 v[184:185], v[232:233], 0, s[30:31]
	s_addc_u32 s11, s25, 0
	s_add_i32 s12, s13, s60
	global_load_lds_dwordx4 v[184:185], off
	v_lshl_add_u64 v[184:185], s[10:11], 0, v[0:1]
	s_mov_b32 m0, s12
	s_nop 0
	global_load_lds_dwordx4 v[184:185], off
	v_lshl_add_u64 v[184:185], s[10:11], 0, v[142:143]
	s_add_i32 m0, s12, 0x2000
	s_nop 0
	global_load_lds_dwordx4 v[184:185], off
	v_lshl_add_u64 v[184:185], v[234:235], 0, s[30:31]
	s_mov_b32 m0, s65
	s_nop 0
	global_load_lds_dwordx4 v[184:185], off
	v_lshl_add_u64 v[184:185], v[236:237], 0, s[30:31]
	s_mov_b32 m0, s66
	s_nop 0
	global_load_lds_dwordx4 v[184:185], off
	s_waitcnt vmcnt(8)
	s_waitcnt lgkmcnt(0)
	s_barrier
	s_setprio 1
	v_mfma_f32_16x16x32_bf16 v[62:65], v[148:151], v[180:183], v[62:65]
	v_mfma_f32_16x16x32_bf16 v[58:61], v[156:159], v[180:183], v[58:61]
	v_mfma_f32_16x16x32_bf16 v[46:49], v[148:151], v[194:197], v[46:49]
	v_mfma_f32_16x16x32_bf16 v[42:45], v[156:159], v[194:197], v[42:45]
	v_mfma_f32_16x16x32_bf16 v[30:33], v[148:151], v[216:219], v[30:33]
	v_mfma_f32_16x16x32_bf16 v[26:29], v[156:159], v[216:219], v[26:29]
	v_mfma_f32_16x16x32_bf16 v[14:17], v[148:151], v[224:227], v[14:17]
	v_mfma_f32_16x16x32_bf16 v[10:13], v[156:159], v[224:227], v[10:13]
	v_mfma_f32_16x16x32_bf16 v[62:65], v[152:155], v[190:193], v[62:65]
	v_mfma_f32_16x16x32_bf16 v[58:61], v[160:163], v[190:193], v[58:61]
	v_mfma_f32_16x16x32_bf16 v[46:49], v[152:155], v[198:201], v[46:49]
	v_mfma_f32_16x16x32_bf16 v[42:45], v[160:163], v[198:201], v[42:45]
	v_mfma_f32_16x16x32_bf16 v[30:33], v[152:155], v[220:223], v[30:33]
	v_mfma_f32_16x16x32_bf16 v[26:29], v[160:163], v[220:223], v[26:29]
	v_mfma_f32_16x16x32_bf16 v[14:17], v[152:155], v[228:231], v[14:17]
	v_mfma_f32_16x16x32_bf16 v[10:13], v[160:163], v[228:231], v[10:13]
	v_mfma_f32_16x16x32_bf16 v[54:57], v[164:167], v[180:183], v[54:57]
	v_mfma_f32_16x16x32_bf16 v[50:53], v[172:175], v[180:183], v[50:53]
	v_mfma_f32_16x16x32_bf16 v[38:41], v[164:167], v[194:197], v[38:41]
	v_mfma_f32_16x16x32_bf16 v[34:37], v[172:175], v[194:197], v[34:37]
	v_mfma_f32_16x16x32_bf16 v[22:25], v[164:167], v[216:219], v[22:25]
	v_mfma_f32_16x16x32_bf16 v[18:21], v[172:175], v[216:219], v[18:21]
	v_mfma_f32_16x16x32_bf16 v[6:9], v[164:167], v[224:227], v[6:9]
	v_mfma_f32_16x16x32_bf16 v[2:5], v[172:175], v[224:227], v[2:5]
	v_mfma_f32_16x16x32_bf16 v[54:57], v[168:171], v[190:193], v[54:57]
	v_mfma_f32_16x16x32_bf16 v[50:53], v[176:179], v[190:193], v[50:53]
	v_mfma_f32_16x16x32_bf16 v[38:41], v[168:171], v[198:201], v[38:41]
	v_mfma_f32_16x16x32_bf16 v[34:37], v[176:179], v[198:201], v[34:37]
	v_mfma_f32_16x16x32_bf16 v[22:25], v[168:171], v[220:223], v[22:25]
	v_mfma_f32_16x16x32_bf16 v[18:21], v[176:179], v[220:223], v[18:21]
	v_mfma_f32_16x16x32_bf16 v[6:9], v[168:171], v[228:231], v[6:9]
	v_mfma_f32_16x16x32_bf16 v[2:5], v[176:179], v[228:231], v[2:5]
	s_setprio 0
	s_barrier
	s_add_i32 s22, s22, 2
	s_add_u32 s14, s14, 0x100
	s_addc_u32 s15, s15, 0
	s_cmp_gt_u32 s22, 29
	s_mov_b64 s[16:17], s[18:19]
	s_cbranch_scc0 .LBB0_601
; __device__ __forceinline__ unsigned cvt_pk_bf16(float lo, float hi) { unsigned r; asm volatile("v_cvt_pk_bf16_f32 %0, %1, %2" : "=v"(r) : "v"(lo), "v"(hi)); return r; }
;     __device__ __forceinline__ void operator()(const f32x4 (&acc)[2][2][4][2], const Unit& u, int wr, int wc, int fr, int fq) const {
;         const int row0 = u.pm * BM + wr * 64 + fr; const int col0 = u.pn * BM + wc * 32 + 4 * fq;
; #pragma unroll
;         for (int ai = 0; ai < 2; ++ai) {
;             u32x2 bv[4][2][2];
; #pragma unroll
;             for (int m = 0; m < 4; ++m) { const size_t off = (size_t)(row0 + ai * HALF + m * 16) * ldc + col0;
; #pragma unroll
;                 for (int bj = 0; bj < 2; ++bj)
; #pragma unroll
;                     for (int n = 0; n < 2; ++n) bv[m][bj][n] = *(const u32x2*)(xb + off + bj * HALF + n * 16); }
;             asm volatile("" ::: "memory");
; #pragma unroll
;             for (int m = 0; m < 4; ++m) {
;                 const int row = row0 + ai * HALF + m * 16;
;                 const size_t off = (size_t)row * ldc + col0;
;                 float s = 0.f;
; #pragma unroll
;                 for (int bj = 0; bj < 2; ++bj)
; #pragma unroll
;                     for (int n = 0; n < 2; ++n) {
;                         const size_t c = off + bj * HALF + n * 16;
;                         const u32x2 w0 = bv[m][bj][n];
;                         const f32x4 b = {__uint_as_float(w0.x << 16), __uint_as_float(w0.x & 0xffff0000u), __uint_as_float(w0.y << 16), __uint_as_float(w0.y & 0xffff0000u)};
;                         const f32x4 o = b + acc[ai][bj][m][n];
;                         if (fin) { *(f32x4*)(outf + c) = o; }
;                         else { u32x2 w; w.x = cvt_pk_bf16(o[0], o[1]); w.y = cvt_pk_bf16(o[2], o[3]); *(u32x2*)(xb + c) = w;
;                                s += (o[0] * o[0] + o[1] * o[1]) + (o[2] * o[2] + o[3] * o[3]); }
;                     }
;                 if (!fin) { s += __shfl_xor(s, 16); s += __shfl_xor(s, 32); if (fq == 0) unsafeAtomicAdd(ssq + row, s); }
	v_lshl_or_b32 v148, s2, 8, v188
	v_lshl_add_u32 v152, s4, 8, v186
	v_ashrrev_i32_e32 v149, 31, v148
	v_lshlrev_b64 v[190:191], 1, v[148:149]
	v_ashrrev_i32_e32 v153, 31, v152
	v_lshl_add_u64 v[150:151], s[48:49], 0, v[190:191]
	v_lshlrev_b64 v[154:155], 12, v[152:153]
	v_lshl_add_u64 v[156:157], v[150:151], 0, v[154:155]
	global_load_dwordx2 v[192:193], v[156:157], off
	global_load_dwordx2 v[194:195], v[156:157], off offset:32
	global_load_dwordx2 v[196:197], v[156:157], off offset:256
	global_load_dwordx2 v[198:199], v[156:157], off offset:288
	v_or_b32_e32 v184, 16, v152
	v_ashrrev_i32_e32 v185, 31, v184
	v_lshlrev_b64 v[156:157], 12, v[184:185]
	v_or_b32_e32 v174, 32, v152
	v_lshl_add_u64 v[156:157], v[150:151], 0, v[156:157]
	v_ashrrev_i32_e32 v175, 31, v174
	global_load_dwordx2 v[182:183], v[156:157], off
	global_load_dwordx2 v[180:181], v[156:157], off offset:32
	global_load_dwordx2 v[178:179], v[156:157], off offset:256
	global_load_dwordx2 v[176:177], v[156:157], off offset:288
	v_lshlrev_b64 v[156:157], 12, v[174:175]
	v_or_b32_e32 v158, 48, v152
	v_lshl_add_u64 v[156:157], v[150:151], 0, v[156:157]
	v_ashrrev_i32_e32 v159, 31, v158
	global_load_dwordx2 v[172:173], v[156:157], off
	global_load_dwordx2 v[170:171], v[156:157], off offset:32
	global_load_dwordx2 v[166:167], v[156:157], off offset:256
	global_load_dwordx2 v[162:163], v[156:157], off offset:288
	v_lshlrev_b64 v[156:157], 12, v[158:159]
	v_lshl_add_u64 v[156:157], v[150:151], 0, v[156:157]
	global_load_dwordx2 v[168:169], v[156:157], off
	global_load_dwordx2 v[164:165], v[156:157], off offset:32
	global_load_dwordx2 v[160:161], v[156:157], off offset:256
	s_nop 0
	global_load_dwordx2 v[156:157], v[156:157], off offset:288
	s_waitcnt vmcnt(0)
	v_lshlrev_b32_e32 v200, 16, v192
	v_and_b32_e32 v201, 0xffff0000, v192
	v_lshlrev_b32_e32 v192, 16, v193
	v_and_b32_e32 v193, 0xffff0000, v193
	v_pk_add_f32 v[126:127], v[126:127], v[200:201]
	v_pk_add_f32 v[128:129], v[128:129], v[192:193]
	v_cvt_pk_bf16_f32 v192, v126, v127
	v_mul_f32_e32 v127, v127, v127
	v_lshl_add_u64 v[200:201], s[48:49], 0, v[154:155]
	v_fmac_f32_e32 v127, v126, v126
	v_mul_f32_e32 v126, v129, v129
	v_lshl_add_u64 v[190:191], v[200:201], 0, v[190:191]
	v_fmac_f32_e32 v126, v128, v128
	v_cvt_pk_bf16_f32 v193, v128, v129
	global_store_dwordx2 v[190:191], v[192:193], off
	v_add_f32_e32 v192, v127, v126
	v_lshlrev_b32_e32 v126, 16, v194
	v_and_b32_e32 v127, 0xffff0000, v194
	v_lshlrev_b32_e32 v128, 16, v195
	v_and_b32_e32 v129, 0xffff0000, v195
	v_pk_add_f32 v[122:123], v[122:123], v[126:127]
	v_pk_add_f32 v[124:125], v[124:125], v[128:129]
	v_cvt_pk_bf16_f32 v126, v122, v123
	v_mul_f32_e32 v123, v123, v123
	v_fmac_f32_e32 v123, v122, v122
	v_mul_f32_e32 v122, v125, v125
	v_fmac_f32_e32 v122, v124, v124
	v_add_f32_e32 v122, v123, v122
	v_cvt_pk_bf16_f32 v127, v124, v125
	global_store_dwordx2 v[190:191], v[126:127], off offset:32
	v_add_f32_e32 v126, v192, v122
	v_lshlrev_b32_e32 v122, 16, v196
	v_and_b32_e32 v123, 0xffff0000, v196
	v_lshlrev_b32_e32 v124, 16, v197
	v_and_b32_e32 v125, 0xffff0000, v197
	v_pk_add_f32 v[118:119], v[118:119], v[122:123]
	v_pk_add_f32 v[120:121], v[120:121], v[124:125]
	v_cvt_pk_bf16_f32 v122, v118, v119
	v_mul_f32_e32 v119, v119, v119
	v_fmac_f32_e32 v119, v118, v118
	v_mul_f32_e32 v118, v121, v121
	v_fmac_f32_e32 v118, v120, v120
	v_add_f32_e32 v118, v119, v118
	v_cvt_pk_bf16_f32 v123, v120, v121
	global_store_dwordx2 v[190:191], v[122:123], off offset:256
	v_add_f32_e32 v122, v126, v118
	v_lshlrev_b32_e32 v118, 16, v198
	v_and_b32_e32 v119, 0xffff0000, v198
	v_lshlrev_b32_e32 v120, 16, v199
	v_and_b32_e32 v121, 0xffff0000, v199
	v_pk_add_f32 v[114:115], v[114:115], v[118:119]
	v_pk_add_f32 v[116:117], v[116:117], v[120:121]
	v_cvt_pk_bf16_f32 v118, v114, v115
	v_mul_f32_e32 v115, v115, v115
	v_fmac_f32_e32 v115, v114, v114
	v_mul_f32_e32 v114, v117, v117
	v_cvt_pk_bf16_f32 v119, v116, v117
	v_fmac_f32_e32 v114, v116, v116
	v_and_b32_e32 v116, 64, v208
	v_add_f32_e32 v114, v115, v114
	v_xor_b32_e32 v115, 16, v208
	v_add_u32_e32 v117, 64, v116
	v_cmp_lt_i32_e32 vcc, v115, v117
	v_add_f32_e32 v114, v122, v114
	global_store_dwordx2 v[190:191], v[118:119], off offset:288
	v_cndmask_b32_e32 v115, v208, v115, vcc
	v_lshlrev_b32_e32 v116, 2, v115
	ds_bpermute_b32 v115, v116, v114
	s_waitcnt lgkmcnt(0)
	v_add_f32_e32 v118, v114, v115
	v_xor_b32_e32 v114, 32, v208
	v_cmp_lt_i32_e32 vcc, v114, v117
	s_nop 1
	v_cndmask_b32_e32 v114, v208, v114, vcc
	v_lshlrev_b32_e32 v117, 2, v114
	ds_bpermute_b32 v119, v117, v118
	v_lshl_add_u64 v[114:115], v[152:153], 2, s[50:51]
	s_and_saveexec_b64 s[16:17], s[42:43]
	s_cbranch_execz .LBB0_604
	s_waitcnt lgkmcnt(0)
	v_add_f32_e32 v118, v118, v119
	global_atomic_add_f32 v[114:115], v118, off

; #define PG8_STAGE(bufoff, gbase, voff) do { _Pragma("unroll") for (int _i = 0; _i < 2; ++_i) \
;         __builtin_amdgcn_global_load_lds((const unsigned*)((const char*)(gbase) + (voff)[_i]), (PG8_LAS unsigned*)(lds + (bufoff) + ldsw + _i * 8192), 16, 0, 0); } while (0)
; #define PG8_LDA(dst, b, h) do { _Pragma("unroll") for (int m = 0; m < 4; ++m) _Pragma("unroll") for (int k = 0; k < 2; ++k) dst[m][k] = *(const PG8_LAS bf16x8*)(lds + PG8_SA(b, h) + aoff + m * 2048 + k * 1024); } while (0)
; #define PG8_LDB(dst, b, h) do { _Pragma("unroll") for (int n = 0; n < 2; ++n) _Pragma("unroll") for (int k = 0; k < 2; ++k) dst[n][k] = *(const PG8_LAS bf16x8*)(lds + PG8_SB(b, h) + boff + n * 2048 + k * 1024); } while (0)
; #define PG8_MMA(ai, bj, At, Bt) do { __builtin_amdgcn_s_setprio(1); _Pragma("unroll") for (int m = 0; m < 4; ++m) _Pragma("unroll") for (int n = 0; n < 2; ++n) _Pragma("unroll") for (int k = 0; k < 2; ++k) \
;         acc[ai][bj][m][n] = __builtin_amdgcn_mfma_f32_16x16x32_bf16(Bt[n][k], At[m][k], acc[ai][bj][m][n], 0, 0, 0); __builtin_amdgcn_s_setprio(0); } while (0)
; #define PG8_WAIT_V(n) asm volatile("s_waitcnt vmcnt(" #n ")" ::: "memory")
; #define PG8_WAIT_L(n) asm volatile("s_waitcnt lgkmcnt(" #n ")" ::: "memory")
; #define PG8_BAR __builtin_amdgcn_s_barrier()
; #define PG8_SCHED __builtin_amdgcn_sched_barrier(0)
; template <class Epi, class Sched, bool ALIGN_EPI = false, bool SP2 = false>
; __device__ __forceinline__ void gemm_phase(PG8_LAS unsigned char* lds, const Gemm g, const Sched& S, const Epi& E) {
;     ...
;             PG8_LDB(B0, 0, 0); PG8_LDB(B1, 0, 1); PG8_SCHED; PG8_LDA(At, 0, 0); PG8_STAGE(PG8_SA(1, 1), a1 + hstep, voffA);
;             PG8_WAIT_V(8); PG8_WAIT_L(0); PG8_BAR; PG8_MMA(0, 0, At, B0); PG8_MMA(0, 1, At, B1); PG8_BAR; PG8_SCHED;
;             PG8_LDA(At, 0, 1); PG8_STAGE(PG8_SB(0, 0), b2, voffB); PG8_STAGE(PG8_SB(0, 1), b2 + hstep, voffB); PG8_STAGE(PG8_SA(0, 0), a2, voffA);
.LBB0_686:
	s_add_u32 s10, s16, 0xfff80080
	s_addc_u32 s11, s17, -1
	s_add_i32 s12, 0, 0x10000
	s_cmp_eq_u32 s22, 28
	s_cselect_b32 s25, s5, s11
	s_cselect_b32 s24, s7, s10
	v_add_u32_e32 v160, s12, v163
	s_cselect_b32 s19, s8, s15
	s_cselect_b32 s18, s9, s14
	s_add_i32 s13, 0, 0x14000
	ds_read_b128 v[152:155], v160
	ds_read_b128 v[156:159], v160 offset:1024
	ds_read_b128 v[166:169], v160 offset:2048
	ds_read_b128 v[170:173], v160 offset:3072
	v_add_u32_e32 v160, s13, v163
	ds_read_b128 v[174:177], v160
	ds_read_b128 v[178:181], v160 offset:1024
	ds_read_b128 v[182:185], v160 offset:2048
	ds_read_b128 v[186:189], v160 offset:3072
	v_lshl_add_u64 v[160:161], s[16:17], 0, v[148:149]
	s_add_i32 m0, s59, 0xc000
	ds_read_b128 v[190:193], v165
	ds_read_b128 v[194:197], v165 offset:1024
	ds_read_b128 v[198:201], v165 offset:2048
	ds_read_b128 v[216:219], v165 offset:3072
	ds_read_b128 v[220:223], v165 offset:4096
	ds_read_b128 v[224:227], v165 offset:5120
	ds_read_b128 v[228:231], v165 offset:6144
	ds_read_b128 v[232:235], v165 offset:7168
	global_load_lds_dwordx4 v[160:161], off
	v_lshl_add_u64 v[160:161], s[16:17], 0, v[150:151]
	s_add_i32 m0, s59, 0xe000
	s_nop 0
	global_load_lds_dwordx4 v[160:161], off
	s_waitcnt vmcnt(8)
	s_waitcnt lgkmcnt(0)
	s_barrier
	s_setprio 1
	v_mfma_f32_16x16x32_bf16 v[126:129], v[152:155], v[190:193], v[126:129]
	v_mfma_f32_16x16x32_bf16 v[122:125], v[166:169], v[190:193], v[122:125]
	v_mfma_f32_16x16x32_bf16 v[110:113], v[152:155], v[198:201], v[110:113]
	v_mfma_f32_16x16x32_bf16 v[106:109], v[166:169], v[198:201], v[106:109]
	v_mfma_f32_16x16x32_bf16 v[94:97], v[152:155], v[220:223], v[94:97]
	v_mfma_f32_16x16x32_bf16 v[90:93], v[166:169], v[220:223], v[90:93]
	v_mfma_f32_16x16x32_bf16 v[78:81], v[152:155], v[228:231], v[78:81]
	v_mfma_f32_16x16x32_bf16 v[74:77], v[166:169], v[228:231], v[74:77]
	v_mfma_f32_16x16x32_bf16 v[126:129], v[156:159], v[194:197], v[126:129]
	v_mfma_f32_16x16x32_bf16 v[122:125], v[170:173], v[194:197], v[122:125]
	v_mfma_f32_16x16x32_bf16 v[110:113], v[156:159], v[216:219], v[110:113]
	v_mfma_f32_16x16x32_bf16 v[106:109], v[170:173], v[216:219], v[106:109]
	v_mfma_f32_16x16x32_bf16 v[94:97], v[156:159], v[224:227], v[94:97]
	v_mfma_f32_16x16x32_bf16 v[90:93], v[170:173], v[224:227], v[90:93]
	v_mfma_f32_16x16x32_bf16 v[78:81], v[156:159], v[232:235], v[78:81]
	v_mfma_f32_16x16x32_bf16 v[74:77], v[170:173], v[232:235], v[74:77]
	v_mfma_f32_16x16x32_bf16 v[118:121], v[174:177], v[190:193], v[118:121]
	v_mfma_f32_16x16x32_bf16 v[114:117], v[182:185], v[190:193], v[114:117]
	v_mfma_f32_16x16x32_bf16 v[102:105], v[174:177], v[198:201], v[102:105]
	v_mfma_f32_16x16x32_bf16 v[98:101], v[182:185], v[198:201], v[98:101]
	v_mfma_f32_16x16x32_bf16 v[86:89], v[174:177], v[220:223], v[86:89]
	v_mfma_f32_16x16x32_bf16 v[82:85], v[182:185], v[220:223], v[82:85]
	v_mfma_f32_16x16x32_bf16 v[70:73], v[174:177], v[228:231], v[70:73]
	v_mfma_f32_16x16x32_bf16 v[66:69], v[182:185], v[228:231], v[66:69]
	v_mfma_f32_16x16x32_bf16 v[118:121], v[178:181], v[194:197], v[118:121]
	v_mfma_f32_16x16x32_bf16 v[114:117], v[186:189], v[194:197], v[114:117]
	v_mfma_f32_16x16x32_bf16 v[102:105], v[178:181], v[216:219], v[102:105]
	v_mfma_f32_16x16x32_bf16 v[98:101], v[186:189], v[216:219], v[98:101]
	v_mfma_f32_16x16x32_bf16 v[86:89], v[178:181], v[224:227], v[86:89]
	v_mfma_f32_16x16x32_bf16 v[82:85], v[186:189], v[224:227], v[82:85]
	v_mfma_f32_16x16x32_bf16 v[70:73], v[178:181], v[232:235], v[70:73]
	v_mfma_f32_16x16x32_bf16 v[66:69], v[186:189], v[232:235], v[66:69]
	s_setprio 0
	s_barrier
	s_add_i32 s10, s12, s58
	v_lshl_add_u64 v[160:161], s[18:19], 0, v[0:1]
	s_mov_b32 m0, s10
	ds_read_b128 v[190:193], v165 offset:16384
	ds_read_b128 v[194:197], v165 offset:17408
	ds_read_b128 v[198:201], v165 offset:18432
	ds_read_b128 v[216:219], v165 offset:19456
	ds_read_b128 v[220:223], v165 offset:20480
	ds_read_b128 v[224:227], v165 offset:21504
	ds_read_b128 v[228:231], v165 offset:22528
	ds_read_b128 v[232:235], v165 offset:23552
	global_load_lds_dwordx4 v[160:161], off
	s_add_i32 m0, s10, 0x2000
	s_add_u32 s10, s18, 0x80000
	v_lshl_add_u64 v[236:237], s[18:19], 0, v[142:143]
	s_addc_u32 s11, s19, 0
	s_add_i32 s12, s13, s58
	global_load_lds_dwordx4 v[236:237], off
	v_lshl_add_u64 v[238:239], s[10:11], 0, v[0:1]
	s_mov_b32 m0, s12
	v_lshl_add_u64 v[240:241], s[24:25], 0, v[144:145]
	global_load_lds_dwordx4 v[238:239], off
	v_lshl_add_u64 v[238:239], s[10:11], 0, v[142:143]
	s_add_i32 m0, s12, 0x2000
	s_nop 0
	global_load_lds_dwordx4 v[238:239], off
	v_lshl_add_u64 v[238:239], s[24:25], 0, v[146:147]
	s_mov_b32 m0, s59
	s_nop 0
	global_load_lds_dwordx4 v[238:239], off
	s_mov_b32 m0, s60
	s_nop 0
	global_load_lds_dwordx4 v[240:241], off
	s_waitcnt vmcnt(8)
	s_waitcnt lgkmcnt(0)
	s_barrier
; #define PG8_STAGE(bufoff, gbase, voff) do { _Pragma("unroll") for (int _i = 0; _i < 2; ++_i) \
;         __builtin_amdgcn_global_load_lds((const unsigned*)((const char*)(gbase) + (voff)[_i]), (PG8_LAS unsigned*)(lds + (bufoff) + ldsw + _i * 8192), 16, 0, 0); } while (0)
; #define PG8_LDA(dst, b, h) do { _Pragma("unroll") for (int m = 0; m < 4; ++m) _Pragma("unroll") for (int k = 0; k < 2; ++k) dst[m][k] = *(const PG8_LAS bf16x8*)(lds + PG8_SA(b, h) + aoff + m * 2048 + k * 1024); } while (0)
; #define PG8_LDB(dst, b, h) do { _Pragma("unroll") for (int n = 0; n < 2; ++n) _Pragma("unroll") for (int k = 0; k < 2; ++k) dst[n][k] = *(const PG8_LAS bf16x8*)(lds + PG8_SB(b, h) + boff + n * 2048 + k * 1024); } while (0)
; #define PG8_MMA(ai, bj, At, Bt) do { __builtin_amdgcn_s_setprio(1); _Pragma("unroll") for (int m = 0; m < 4; ++m) _Pragma("unroll") for (int n = 0; n < 2; ++n) _Pragma("unroll") for (int k = 0; k < 2; ++k) \
;         acc[ai][bj][m][n] = __builtin_amdgcn_mfma_f32_16x16x32_bf16(Bt[n][k], At[m][k], acc[ai][bj][m][n], 0, 0, 0); __builtin_amdgcn_s_setprio(0); } while (0)
; #define PG8_WAIT_V(n) asm volatile("s_waitcnt vmcnt(" #n ")" ::: "memory")
; #define PG8_WAIT_L(n) asm volatile("s_waitcnt lgkmcnt(" #n ")" ::: "memory")
; #define PG8_BAR __builtin_amdgcn_s_barrier()
; #define PG8_SCHED __builtin_amdgcn_sched_barrier(0)
; template <class Epi, class Sched, bool ALIGN_EPI = false, bool SP2 = false>
; __device__ __forceinline__ void gemm_phase(PG8_LAS unsigned char* lds, const Gemm g, const Sched& S, const Epi& E) {
;     ...
;             PG8_WAIT_V(8); PG8_WAIT_L(0); PG8_BAR; PG8_MMA(1, 0, At, B0); PG8_MMA(1, 1, At, B1); PG8_BAR; PG8_SCHED;
;             PG8_LDB(B0, 1, 0); PG8_LDB(B1, 1, 1); PG8_SCHED; PG8_LDA(At, 1, 0); PG8_STAGE(PG8_SA(0, 1), a2 + hstep, voffA);
;             PG8_WAIT_V(8); PG8_WAIT_L(0); PG8_BAR; PG8_MMA(0, 0, At, B0); PG8_MMA(0, 1, At, B1); PG8_BAR; PG8_SCHED;
	s_setprio 1
	v_mfma_f32_16x16x32_bf16 v[62:65], v[152:155], v[190:193], v[62:65]
	v_mfma_f32_16x16x32_bf16 v[58:61], v[166:169], v[190:193], v[58:61]
	v_mfma_f32_16x16x32_bf16 v[46:49], v[152:155], v[198:201], v[46:49]
	v_mfma_f32_16x16x32_bf16 v[42:45], v[166:169], v[198:201], v[42:45]
	v_mfma_f32_16x16x32_bf16 v[30:33], v[152:155], v[220:223], v[30:33]
	v_mfma_f32_16x16x32_bf16 v[26:29], v[166:169], v[220:223], v[26:29]
	v_mfma_f32_16x16x32_bf16 v[14:17], v[152:155], v[228:231], v[14:17]
	v_mfma_f32_16x16x32_bf16 v[10:13], v[166:169], v[228:231], v[10:13]
	v_mfma_f32_16x16x32_bf16 v[62:65], v[156:159], v[194:197], v[62:65]
	v_mfma_f32_16x16x32_bf16 v[58:61], v[170:173], v[194:197], v[58:61]
	v_mfma_f32_16x16x32_bf16 v[46:49], v[156:159], v[216:219], v[46:49]
	v_mfma_f32_16x16x32_bf16 v[42:45], v[170:173], v[216:219], v[42:45]
	v_mfma_f32_16x16x32_bf16 v[30:33], v[156:159], v[224:227], v[30:33]
	v_mfma_f32_16x16x32_bf16 v[26:29], v[170:173], v[224:227], v[26:29]
	v_mfma_f32_16x16x32_bf16 v[14:17], v[156:159], v[232:235], v[14:17]
	v_mfma_f32_16x16x32_bf16 v[10:13], v[170:173], v[232:235], v[10:13]
	v_mfma_f32_16x16x32_bf16 v[54:57], v[174:177], v[190:193], v[54:57]
	v_mfma_f32_16x16x32_bf16 v[50:53], v[182:185], v[190:193], v[50:53]
	v_mfma_f32_16x16x32_bf16 v[38:41], v[174:177], v[198:201], v[38:41]
	v_mfma_f32_16x16x32_bf16 v[34:37], v[182:185], v[198:201], v[34:37]
	v_mfma_f32_16x16x32_bf16 v[22:25], v[174:177], v[220:223], v[22:25]
	v_mfma_f32_16x16x32_bf16 v[18:21], v[182:185], v[220:223], v[18:21]
	v_mfma_f32_16x16x32_bf16 v[6:9], v[174:177], v[228:231], v[6:9]
	v_mfma_f32_16x16x32_bf16 v[2:5], v[182:185], v[228:231], v[2:5]
	v_mfma_f32_16x16x32_bf16 v[54:57], v[178:181], v[194:197], v[54:57]
	v_mfma_f32_16x16x32_bf16 v[50:53], v[186:189], v[194:197], v[50:53]
	v_mfma_f32_16x16x32_bf16 v[38:41], v[178:181], v[216:219], v[38:41]
	v_mfma_f32_16x16x32_bf16 v[34:37], v[186:189], v[216:219], v[34:37]
	v_mfma_f32_16x16x32_bf16 v[22:25], v[178:181], v[224:227], v[22:25]
	v_mfma_f32_16x16x32_bf16 v[18:21], v[186:189], v[224:227], v[18:21]
	v_mfma_f32_16x16x32_bf16 v[6:9], v[178:181], v[232:235], v[6:9]
	v_mfma_f32_16x16x32_bf16 v[2:5], v[186:189], v[232:235], v[2:5]
	s_setprio 0
	s_barrier
	s_add_i32 s12, 0, 0x18000
	s_add_i32 s13, 0, 0x1c000
	v_add_u32_e32 v170, s12, v163
	v_add_u32_e32 v186, s13, v163
	ds_read_b128 v[152:155], v170
	ds_read_b128 v[156:159], v170 offset:1024
	ds_read_b128 v[166:169], v170 offset:2048
	ds_read_b128 v[170:173], v170 offset:3072
	ds_read_b128 v[174:177], v186
	ds_read_b128 v[178:181], v186 offset:1024
	ds_read_b128 v[182:185], v186 offset:2048
	ds_read_b128 v[186:189], v186 offset:3072
	s_add_u32 s10, s24, 0x80000
	s_addc_u32 s11, s25, 0
	s_mov_b32 m0, s61
	v_lshl_add_u64 v[242:243], s[10:11], 0, v[146:147]
	ds_read_b128 v[190:193], v165 offset:32768
	ds_read_b128 v[194:197], v165 offset:33792
	ds_read_b128 v[198:201], v165 offset:34816
	ds_read_b128 v[216:219], v165 offset:35840
	ds_read_b128 v[220:223], v165 offset:36864
	ds_read_b128 v[224:227], v165 offset:37888
	ds_read_b128 v[228:231], v165 offset:38912
	ds_read_b128 v[232:235], v165 offset:39936
	global_load_lds_dwordx4 v[242:243], off
	v_lshl_add_u64 v[242:243], s[10:11], 0, v[144:145]
	s_mov_b32 m0, s62
	s_nop 0
	global_load_lds_dwordx4 v[242:243], off
	s_waitcnt vmcnt(8)
	s_waitcnt lgkmcnt(0)
	s_barrier
	s_setprio 1
	v_mfma_f32_16x16x32_bf16 v[126:129], v[152:155], v[190:193], v[126:129]
	v_mfma_f32_16x16x32_bf16 v[122:125], v[166:169], v[190:193], v[122:125]
	v_mfma_f32_16x16x32_bf16 v[110:113], v[152:155], v[198:201], v[110:113]
	v_mfma_f32_16x16x32_bf16 v[106:109], v[166:169], v[198:201], v[106:109]
	v_mfma_f32_16x16x32_bf16 v[94:97], v[152:155], v[220:223], v[94:97]
	v_mfma_f32_16x16x32_bf16 v[90:93], v[166:169], v[220:223], v[90:93]
	v_mfma_f32_16x16x32_bf16 v[78:81], v[152:155], v[228:231], v[78:81]
	v_mfma_f32_16x16x32_bf16 v[74:77], v[166:169], v[228:231], v[74:77]
	v_mfma_f32_16x16x32_bf16 v[126:129], v[156:159], v[194:197], v[126:129]
	v_mfma_f32_16x16x32_bf16 v[122:125], v[170:173], v[194:197], v[122:125]
	v_mfma_f32_16x16x32_bf16 v[110:113], v[156:159], v[216:219], v[110:113]
	v_mfma_f32_16x16x32_bf16 v[106:109], v[170:173], v[216:219], v[106:109]
	v_mfma_f32_16x16x32_bf16 v[94:97], v[156:159], v[224:227], v[94:97]
	v_mfma_f32_16x16x32_bf16 v[90:93], v[170:173], v[224:227], v[90:93]
	v_mfma_f32_16x16x32_bf16 v[78:81], v[156:159], v[232:235], v[78:81]
	v_mfma_f32_16x16x32_bf16 v[74:77], v[170:173], v[232:235], v[74:77]
	v_mfma_f32_16x16x32_bf16 v[118:121], v[174:177], v[190:193], v[118:121]
	v_mfma_f32_16x16x32_bf16 v[114:117], v[182:185], v[190:193], v[114:117]
	v_mfma_f32_16x16x32_bf16 v[102:105], v[174:177], v[198:201], v[102:105]
	v_mfma_f32_16x16x32_bf16 v[98:101], v[182:185], v[198:201], v[98:101]
	v_mfma_f32_16x16x32_bf16 v[86:89], v[174:177], v[220:223], v[86:89]
	v_mfma_f32_16x16x32_bf16 v[82:85], v[182:185], v[220:223], v[82:85]
	v_mfma_f32_16x16x32_bf16 v[70:73], v[174:177], v[228:231], v[70:73]
	v_mfma_f32_16x16x32_bf16 v[66:69], v[182:185], v[228:231], v[66:69]
	v_mfma_f32_16x16x32_bf16 v[118:121], v[178:181], v[194:197], v[118:121]
	v_mfma_f32_16x16x32_bf16 v[114:117], v[186:189], v[194:197], v[114:117]
	v_mfma_f32_16x16x32_bf16 v[102:105], v[178:181], v[216:219], v[102:105]
	v_mfma_f32_16x16x32_bf16 v[98:101], v[186:189], v[216:219], v[98:101]
	v_mfma_f32_16x16x32_bf16 v[86:89], v[178:181], v[224:227], v[86:89]
	v_mfma_f32_16x16x32_bf16 v[82:85], v[186:189], v[224:227], v[82:85]
	v_mfma_f32_16x16x32_bf16 v[70:73], v[178:181], v[232:235], v[70:73]
	v_mfma_f32_16x16x32_bf16 v[66:69], v[186:189], v[232:235], v[66:69]
	s_setprio 0
	s_barrier
; #define PG8_STAGE(bufoff, gbase, voff) do { _Pragma("unroll") for (int _i = 0; _i < 2; ++_i) \
;         __builtin_amdgcn_global_load_lds((const unsigned*)((const char*)(gbase) + (voff)[_i]), (PG8_LAS unsigned*)(lds + (bufoff) + ldsw + _i * 8192), 16, 0, 0); } while (0)
; #define PG8_LDA(dst, b, h) do { _Pragma("unroll") for (int m = 0; m < 4; ++m) _Pragma("unroll") for (int k = 0; k < 2; ++k) dst[m][k] = *(const PG8_LAS bf16x8*)(lds + PG8_SA(b, h) + aoff + m * 2048 + k * 1024); } while (0)
; #define PG8_MMA(ai, bj, At, Bt) do { __builtin_amdgcn_s_setprio(1); _Pragma("unroll") for (int m = 0; m < 4; ++m) _Pragma("unroll") for (int n = 0; n < 2; ++n) _Pragma("unroll") for (int k = 0; k < 2; ++k) \
;         acc[ai][bj][m][n] = __builtin_amdgcn_mfma_f32_16x16x32_bf16(Bt[n][k], At[m][k], acc[ai][bj][m][n], 0, 0, 0); __builtin_amdgcn_s_setprio(0); } while (0)
; #define PG8_WAIT_V(n) asm volatile("s_waitcnt vmcnt(" #n ")" ::: "memory")
; #define PG8_WAIT_L(n) asm volatile("s_waitcnt lgkmcnt(" #n ")" ::: "memory")
; #define PG8_BAR __builtin_amdgcn_s_barrier()
; #define PG8_SCHED __builtin_amdgcn_sched_barrier(0)
; template <class Epi, class Sched, bool ALIGN_EPI = false, bool SP2 = false>
; __device__ __forceinline__ void gemm_phase(PG8_LAS unsigned char* lds, const Gemm g, const Sched& S, const Epi& E) {
;     ...
;             PG8_LDA(At, 1, 1); PG8_STAGE(PG8_SB(1, 0), b3, voffB); PG8_STAGE(PG8_SB(1, 1), b3 + hstep, voffB); PG8_STAGE(PG8_SA(1, 0), a3, voffA);
;             PG8_WAIT_V(8); PG8_WAIT_L(0); PG8_BAR; PG8_MMA(1, 0, At, B0); PG8_MMA(1, 1, At, B1); PG8_BAR; PG8_SCHED;
;     ...
;         if constexpr (ALIGN_EPI) { if (wr == 0) PG8_BAR; }
	s_add_i32 s10, s12, s58
	v_lshl_add_u64 v[160:161], v[160:161], 0, s[30:31]
	s_mov_b32 m0, s10
	ds_read_b128 v[190:193], v165 offset:49152
	ds_read_b128 v[194:197], v165 offset:50176
	ds_read_b128 v[198:201], v165 offset:51200
	ds_read_b128 v[216:219], v165 offset:52224
	ds_read_b128 v[220:223], v165 offset:53248
	ds_read_b128 v[224:227], v165 offset:54272
	ds_read_b128 v[228:231], v165 offset:55296
	ds_read_b128 v[232:235], v165 offset:56320
	global_load_lds_dwordx4 v[160:161], off
	s_add_i32 m0, s10, 0x2000
	s_add_u32 s10, s18, 0x80080
	v_lshl_add_u64 v[160:161], v[236:237], 0, s[30:31]
	s_addc_u32 s11, s19, 0
	s_add_i32 s12, s13, s58
	global_load_lds_dwordx4 v[160:161], off
	v_lshl_add_u64 v[160:161], s[10:11], 0, v[0:1]
	s_mov_b32 m0, s12
	s_nop 0
	global_load_lds_dwordx4 v[160:161], off
	v_lshl_add_u64 v[160:161], s[10:11], 0, v[142:143]
	s_add_i32 m0, s12, 0x2000
	s_nop 0
	global_load_lds_dwordx4 v[160:161], off
	v_lshl_add_u64 v[160:161], v[238:239], 0, s[30:31]
	s_mov_b32 m0, s63
	s_nop 0
	global_load_lds_dwordx4 v[160:161], off
	v_lshl_add_u64 v[160:161], v[240:241], 0, s[30:31]
	s_mov_b32 m0, s64
	s_nop 0
	global_load_lds_dwordx4 v[160:161], off
	s_waitcnt vmcnt(8)
	s_waitcnt lgkmcnt(0)
	s_barrier
	s_setprio 1
	v_mfma_f32_16x16x32_bf16 v[62:65], v[152:155], v[190:193], v[62:65]
	v_mfma_f32_16x16x32_bf16 v[58:61], v[166:169], v[190:193], v[58:61]
	v_mfma_f32_16x16x32_bf16 v[46:49], v[152:155], v[198:201], v[46:49]
	v_mfma_f32_16x16x32_bf16 v[42:45], v[166:169], v[198:201], v[42:45]
	v_mfma_f32_16x16x32_bf16 v[30:33], v[152:155], v[220:223], v[30:33]
	v_mfma_f32_16x16x32_bf16 v[26:29], v[166:169], v[220:223], v[26:29]
	v_mfma_f32_16x16x32_bf16 v[14:17], v[152:155], v[228:231], v[14:17]
	v_mfma_f32_16x16x32_bf16 v[10:13], v[166:169], v[228:231], v[10:13]
	v_mfma_f32_16x16x32_bf16 v[62:65], v[156:159], v[194:197], v[62:65]
	v_mfma_f32_16x16x32_bf16 v[58:61], v[170:173], v[194:197], v[58:61]
	v_mfma_f32_16x16x32_bf16 v[46:49], v[156:159], v[216:219], v[46:49]
	v_mfma_f32_16x16x32_bf16 v[42:45], v[170:173], v[216:219], v[42:45]
	v_mfma_f32_16x16x32_bf16 v[30:33], v[156:159], v[224:227], v[30:33]
	v_mfma_f32_16x16x32_bf16 v[26:29], v[170:173], v[224:227], v[26:29]
	v_mfma_f32_16x16x32_bf16 v[14:17], v[156:159], v[232:235], v[14:17]
	v_mfma_f32_16x16x32_bf16 v[10:13], v[170:173], v[232:235], v[10:13]
	v_mfma_f32_16x16x32_bf16 v[54:57], v[174:177], v[190:193], v[54:57]
	v_mfma_f32_16x16x32_bf16 v[50:53], v[182:185], v[190:193], v[50:53]
	v_mfma_f32_16x16x32_bf16 v[38:41], v[174:177], v[198:201], v[38:41]
	v_mfma_f32_16x16x32_bf16 v[34:37], v[182:185], v[198:201], v[34:37]
	v_mfma_f32_16x16x32_bf16 v[22:25], v[174:177], v[220:223], v[22:25]
	v_mfma_f32_16x16x32_bf16 v[18:21], v[182:185], v[220:223], v[18:21]
	v_mfma_f32_16x16x32_bf16 v[6:9], v[174:177], v[228:231], v[6:9]
	v_mfma_f32_16x16x32_bf16 v[2:5], v[182:185], v[228:231], v[2:5]
	v_mfma_f32_16x16x32_bf16 v[54:57], v[178:181], v[194:197], v[54:57]
	v_mfma_f32_16x16x32_bf16 v[50:53], v[186:189], v[194:197], v[50:53]
	v_mfma_f32_16x16x32_bf16 v[38:41], v[178:181], v[216:219], v[38:41]
	v_mfma_f32_16x16x32_bf16 v[34:37], v[186:189], v[216:219], v[34:37]
	v_mfma_f32_16x16x32_bf16 v[22:25], v[178:181], v[224:227], v[22:25]
	v_mfma_f32_16x16x32_bf16 v[18:21], v[186:189], v[224:227], v[18:21]
	v_mfma_f32_16x16x32_bf16 v[6:9], v[178:181], v[232:235], v[6:9]
	v_mfma_f32_16x16x32_bf16 v[2:5], v[186:189], v[232:235], v[2:5]
	s_setprio 0
	s_barrier
	s_add_i32 s22, s22, 2
	s_add_u32 s16, s16, 0x100
	s_addc_u32 s17, s17, 0
	s_add_u32 s14, s14, 0x100
	s_addc_u32 s15, s15, 0
	s_cmp_gt_u32 s22, 29
	s_cbranch_scc0 .LBB0_686
	s_and_b64 vcc, exec, s[50:51]
	s_cbranch_vccz .LBB0_689
	s_barrier

; #define PG8_STAGE(bufoff, gbase, voff) do { _Pragma("unroll") for (int _i = 0; _i < 2; ++_i) \
;         __builtin_amdgcn_global_load_lds((const unsigned*)((const char*)(gbase) + (voff)[_i]), (PG8_LAS unsigned*)(lds + (bufoff) + ldsw + _i * 8192), 16, 0, 0); } while (0)
; #define PG8_LDA(dst, b, h) do { _Pragma("unroll") for (int m = 0; m < 4; ++m) _Pragma("unroll") for (int k = 0; k < 2; ++k) dst[m][k] = *(const PG8_LAS bf16x8*)(lds + PG8_SA(b, h) + aoff + m * 2048 + k * 1024); } while (0)
; #define PG8_LDB(dst, b, h) do { _Pragma("unroll") for (int n = 0; n < 2; ++n) _Pragma("unroll") for (int k = 0; k < 2; ++k) dst[n][k] = *(const PG8_LAS bf16x8*)(lds + PG8_SB(b, h) + boff + n * 2048 + k * 1024); } while (0)
; #define PG8_MMA(ai, bj, At, Bt) do { __builtin_amdgcn_s_setprio(1); _Pragma("unroll") for (int m = 0; m < 4; ++m) _Pragma("unroll") for (int n = 0; n < 2; ++n) _Pragma("unroll") for (int k = 0; k < 2; ++k) \
;         acc[ai][bj][m][n] = __builtin_amdgcn_mfma_f32_16x16x32_bf16(Bt[n][k], At[m][k], acc[ai][bj][m][n], 0, 0, 0); __builtin_amdgcn_s_setprio(0); } while (0)
; #define PG8_WAIT_V(n) asm volatile("s_waitcnt vmcnt(" #n ")" ::: "memory")
; #define PG8_WAIT_L(n) asm volatile("s_waitcnt lgkmcnt(" #n ")" ::: "memory")
; #define PG8_BAR __builtin_amdgcn_s_barrier()
; #define PG8_SCHED __builtin_amdgcn_sched_barrier(0)
; template <class Epi, class Sched, bool ALIGN_EPI = false, bool SP2 = false>
; __device__ __forceinline__ void gemm_phase(PG8_LAS unsigned char* lds, const Gemm g, const Sched& S, const Epi& E) {
;     ...
;             PG8_LDB(B0, 0, 0); PG8_LDB(B1, 0, 1); PG8_SCHED; PG8_LDA(At, 0, 0); PG8_STAGE(PG8_SA(1, 1), a1 + hstep, voffA);
;             PG8_WAIT_V(8); PG8_WAIT_L(0); PG8_BAR; PG8_MMA(0, 0, At, B0); PG8_MMA(0, 1, At, B1); PG8_BAR; PG8_SCHED;
;             PG8_LDA(At, 0, 1); PG8_STAGE(PG8_SB(0, 0), b2, voffB); PG8_STAGE(PG8_SB(0, 1), b2 + hstep, voffB); PG8_STAGE(PG8_SA(0, 0), a2, voffA);
.LBB0_758:
	s_add_u32 s18, s16, 0x100
	s_addc_u32 s19, s17, 0
	s_add_i32 s10, 0, 0x10000
	s_cmpk_eq_i32 s22, 0x7c
	s_cselect_b32 s27, s5, s19
	s_cselect_b32 s26, s7, s18
	s_cselect_b32 s25, s8, s15
	s_cselect_b32 s24, s9, s14
	s_add_i32 s12, 0, 0x14000
	v_add_u32_e32 v160, s10, v216
	v_add_u32_e32 v176, s12, v216
	ds_read_b128 v[148:151], v160
	ds_read_b128 v[152:155], v160 offset:1024
	ds_read_b128 v[156:159], v160 offset:2048
	ds_read_b128 v[160:163], v160 offset:3072
	ds_read_b128 v[164:167], v176
	ds_read_b128 v[168:171], v176 offset:1024
	ds_read_b128 v[172:175], v176 offset:2048
	ds_read_b128 v[176:179], v176 offset:3072
	v_lshl_add_u64 v[200:201], s[16:17], 0, v[144:145]
	s_add_i32 m0, s64, 0xc000
	ds_read_b128 v[180:183], v218
	ds_read_b128 v[184:187], v218 offset:1024
	ds_read_b128 v[188:191], v218 offset:2048
	ds_read_b128 v[192:195], v218 offset:3072
	ds_read_b128 v[196:199], v218 offset:4096
	ds_read_b128 v[220:223], v218 offset:5120
	ds_read_b128 v[224:227], v218 offset:6144
	ds_read_b128 v[228:231], v218 offset:7168
	global_load_lds_dwordx4 v[200:201], off
	v_lshl_add_u64 v[200:201], s[16:17], 0, v[146:147]
	s_add_i32 m0, s64, 0xe000
	s_nop 0
	global_load_lds_dwordx4 v[200:201], off
	s_waitcnt vmcnt(8)
	s_waitcnt lgkmcnt(0)
	s_barrier
	s_setprio 1
	v_mfma_f32_16x16x32_bf16 v[126:129], v[148:151], v[180:183], v[126:129]
	v_mfma_f32_16x16x32_bf16 v[122:125], v[156:159], v[180:183], v[122:125]
	v_mfma_f32_16x16x32_bf16 v[110:113], v[148:151], v[188:191], v[110:113]
	v_mfma_f32_16x16x32_bf16 v[106:109], v[156:159], v[188:191], v[106:109]
	v_mfma_f32_16x16x32_bf16 v[94:97], v[148:151], v[196:199], v[94:97]
	v_mfma_f32_16x16x32_bf16 v[90:93], v[156:159], v[196:199], v[90:93]
	v_mfma_f32_16x16x32_bf16 v[78:81], v[148:151], v[224:227], v[78:81]
	v_mfma_f32_16x16x32_bf16 v[74:77], v[156:159], v[224:227], v[74:77]
	v_mfma_f32_16x16x32_bf16 v[126:129], v[152:155], v[184:187], v[126:129]
	v_mfma_f32_16x16x32_bf16 v[122:125], v[160:163], v[184:187], v[122:125]
	v_mfma_f32_16x16x32_bf16 v[110:113], v[152:155], v[192:195], v[110:113]
	v_mfma_f32_16x16x32_bf16 v[106:109], v[160:163], v[192:195], v[106:109]
	v_mfma_f32_16x16x32_bf16 v[94:97], v[152:155], v[220:223], v[94:97]
	v_mfma_f32_16x16x32_bf16 v[90:93], v[160:163], v[220:223], v[90:93]
	v_mfma_f32_16x16x32_bf16 v[78:81], v[152:155], v[228:231], v[78:81]
	v_mfma_f32_16x16x32_bf16 v[74:77], v[160:163], v[228:231], v[74:77]
	v_mfma_f32_16x16x32_bf16 v[118:121], v[164:167], v[180:183], v[118:121]
	v_mfma_f32_16x16x32_bf16 v[114:117], v[172:175], v[180:183], v[114:117]
	v_mfma_f32_16x16x32_bf16 v[102:105], v[164:167], v[188:191], v[102:105]
	v_mfma_f32_16x16x32_bf16 v[98:101], v[172:175], v[188:191], v[98:101]
	v_mfma_f32_16x16x32_bf16 v[86:89], v[164:167], v[196:199], v[86:89]
	v_mfma_f32_16x16x32_bf16 v[82:85], v[172:175], v[196:199], v[82:85]
	v_mfma_f32_16x16x32_bf16 v[70:73], v[164:167], v[224:227], v[70:73]
	v_mfma_f32_16x16x32_bf16 v[66:69], v[172:175], v[224:227], v[66:69]
	v_mfma_f32_16x16x32_bf16 v[118:121], v[168:171], v[184:187], v[118:121]
	v_mfma_f32_16x16x32_bf16 v[114:117], v[176:179], v[184:187], v[114:117]
	v_mfma_f32_16x16x32_bf16 v[102:105], v[168:171], v[192:195], v[102:105]
	v_mfma_f32_16x16x32_bf16 v[98:101], v[176:179], v[192:195], v[98:101]
	v_mfma_f32_16x16x32_bf16 v[86:89], v[168:171], v[220:223], v[86:89]
	v_mfma_f32_16x16x32_bf16 v[82:85], v[176:179], v[220:223], v[82:85]
	v_mfma_f32_16x16x32_bf16 v[70:73], v[168:171], v[228:231], v[70:73]
	v_mfma_f32_16x16x32_bf16 v[66:69], v[176:179], v[228:231], v[66:69]
	s_setprio 0
	s_barrier
	s_add_i32 s10, s10, s63
	v_lshl_add_u64 v[200:201], s[24:25], 0, v[0:1]
	s_mov_b32 m0, s10
	ds_read_b128 v[180:183], v218 offset:16384
	ds_read_b128 v[184:187], v218 offset:17408
	ds_read_b128 v[188:191], v218 offset:18432
	ds_read_b128 v[192:195], v218 offset:19456
	ds_read_b128 v[196:199], v218 offset:20480
	ds_read_b128 v[220:223], v218 offset:21504
	ds_read_b128 v[224:227], v218 offset:22528
	ds_read_b128 v[228:231], v218 offset:23552
	global_load_lds_dwordx4 v[200:201], off
	s_add_i32 m0, s10, 0x2000
	s_add_u32 s10, s24, 0x200000
	v_lshl_add_u64 v[232:233], s[24:25], 0, v[142:143]
	s_addc_u32 s11, s25, 0
	s_add_i32 s12, s12, s63
	global_load_lds_dwordx4 v[232:233], off
	v_lshl_add_u64 v[234:235], s[10:11], 0, v[0:1]
	s_mov_b32 m0, s12
	v_lshl_add_u64 v[236:237], s[26:27], 0, v[142:143]
	global_load_lds_dwordx4 v[234:235], off
	v_lshl_add_u64 v[234:235], s[10:11], 0, v[142:143]
	s_add_i32 m0, s12, 0x2000
	s_nop 0
	global_load_lds_dwordx4 v[234:235], off
	v_lshl_add_u64 v[234:235], s[26:27], 0, v[0:1]
	s_mov_b32 m0, s64
	s_nop 0
	global_load_lds_dwordx4 v[234:235], off
	s_mov_b32 m0, s65
	s_nop 0
	global_load_lds_dwordx4 v[236:237], off
	s_waitcnt vmcnt(8)
	s_waitcnt lgkmcnt(0)
	s_barrier
; #define PG8_STAGE(bufoff, gbase, voff) do { _Pragma("unroll") for (int _i = 0; _i < 2; ++_i) \
;         __builtin_amdgcn_global_load_lds((const unsigned*)((const char*)(gbase) + (voff)[_i]), (PG8_LAS unsigned*)(lds + (bufoff) + ldsw + _i * 8192), 16, 0, 0); } while (0)
; #define PG8_LDA(dst, b, h) do { _Pragma("unroll") for (int m = 0; m < 4; ++m) _Pragma("unroll") for (int k = 0; k < 2; ++k) dst[m][k] = *(const PG8_LAS bf16x8*)(lds + PG8_SA(b, h) + aoff + m * 2048 + k * 1024); } while (0)
; #define PG8_LDB(dst, b, h) do { _Pragma("unroll") for (int n = 0; n < 2; ++n) _Pragma("unroll") for (int k = 0; k < 2; ++k) dst[n][k] = *(const PG8_LAS bf16x8*)(lds + PG8_SB(b, h) + boff + n * 2048 + k * 1024); } while (0)
; #define PG8_MMA(ai, bj, At, Bt) do { __builtin_amdgcn_s_setprio(1); _Pragma("unroll") for (int m = 0; m < 4; ++m) _Pragma("unroll") for (int n = 0; n < 2; ++n) _Pragma("unroll") for (int k = 0; k < 2; ++k) \
;         acc[ai][bj][m][n] = __builtin_amdgcn_mfma_f32_16x16x32_bf16(Bt[n][k], At[m][k], acc[ai][bj][m][n], 0, 0, 0); __builtin_amdgcn_s_setprio(0); } while (0)
; #define PG8_WAIT_V(n) asm volatile("s_waitcnt vmcnt(" #n ")" ::: "memory")
; #define PG8_WAIT_L(n) asm volatile("s_waitcnt lgkmcnt(" #n ")" ::: "memory")
; #define PG8_BAR __builtin_amdgcn_s_barrier()
; #define PG8_SCHED __builtin_amdgcn_sched_barrier(0)
; template <class Epi, class Sched, bool ALIGN_EPI = false, bool SP2 = false>
; __device__ __forceinline__ void gemm_phase(PG8_LAS unsigned char* lds, const Gemm g, const Sched& S, const Epi& E) {
;     ...
;             PG8_WAIT_V(8); PG8_WAIT_L(0); PG8_BAR; PG8_MMA(1, 0, At, B0); PG8_MMA(1, 1, At, B1); PG8_BAR; PG8_SCHED;
;             PG8_LDB(B0, 1, 0); PG8_LDB(B1, 1, 1); PG8_SCHED; PG8_LDA(At, 1, 0); PG8_STAGE(PG8_SA(0, 1), a2 + hstep, voffA);
;             PG8_WAIT_V(8); PG8_WAIT_L(0); PG8_BAR; PG8_MMA(0, 0, At, B0); PG8_MMA(0, 1, At, B1); PG8_BAR; PG8_SCHED;
	s_setprio 1
	v_mfma_f32_16x16x32_bf16 v[62:65], v[148:151], v[180:183], v[62:65]
	v_mfma_f32_16x16x32_bf16 v[58:61], v[156:159], v[180:183], v[58:61]
	v_mfma_f32_16x16x32_bf16 v[46:49], v[148:151], v[188:191], v[46:49]
	v_mfma_f32_16x16x32_bf16 v[42:45], v[156:159], v[188:191], v[42:45]
	v_mfma_f32_16x16x32_bf16 v[30:33], v[148:151], v[196:199], v[30:33]
	v_mfma_f32_16x16x32_bf16 v[26:29], v[156:159], v[196:199], v[26:29]
	v_mfma_f32_16x16x32_bf16 v[14:17], v[148:151], v[224:227], v[14:17]
	v_mfma_f32_16x16x32_bf16 v[10:13], v[156:159], v[224:227], v[10:13]
	v_mfma_f32_16x16x32_bf16 v[62:65], v[152:155], v[184:187], v[62:65]
	v_mfma_f32_16x16x32_bf16 v[58:61], v[160:163], v[184:187], v[58:61]
	v_mfma_f32_16x16x32_bf16 v[46:49], v[152:155], v[192:195], v[46:49]
	v_mfma_f32_16x16x32_bf16 v[42:45], v[160:163], v[192:195], v[42:45]
	v_mfma_f32_16x16x32_bf16 v[30:33], v[152:155], v[220:223], v[30:33]
	v_mfma_f32_16x16x32_bf16 v[26:29], v[160:163], v[220:223], v[26:29]
	v_mfma_f32_16x16x32_bf16 v[14:17], v[152:155], v[228:231], v[14:17]
	v_mfma_f32_16x16x32_bf16 v[10:13], v[160:163], v[228:231], v[10:13]
	v_mfma_f32_16x16x32_bf16 v[54:57], v[164:167], v[180:183], v[54:57]
	v_mfma_f32_16x16x32_bf16 v[50:53], v[172:175], v[180:183], v[50:53]
	v_mfma_f32_16x16x32_bf16 v[38:41], v[164:167], v[188:191], v[38:41]
	v_mfma_f32_16x16x32_bf16 v[34:37], v[172:175], v[188:191], v[34:37]
	v_mfma_f32_16x16x32_bf16 v[22:25], v[164:167], v[196:199], v[22:25]
	v_mfma_f32_16x16x32_bf16 v[18:21], v[172:175], v[196:199], v[18:21]
	v_mfma_f32_16x16x32_bf16 v[6:9], v[164:167], v[224:227], v[6:9]
	v_mfma_f32_16x16x32_bf16 v[2:5], v[172:175], v[224:227], v[2:5]
	v_mfma_f32_16x16x32_bf16 v[54:57], v[168:171], v[184:187], v[54:57]
	v_mfma_f32_16x16x32_bf16 v[50:53], v[176:179], v[184:187], v[50:53]
	v_mfma_f32_16x16x32_bf16 v[38:41], v[168:171], v[192:195], v[38:41]
	v_mfma_f32_16x16x32_bf16 v[34:37], v[176:179], v[192:195], v[34:37]
	v_mfma_f32_16x16x32_bf16 v[22:25], v[168:171], v[220:223], v[22:25]
	v_mfma_f32_16x16x32_bf16 v[18:21], v[176:179], v[220:223], v[18:21]
	v_mfma_f32_16x16x32_bf16 v[6:9], v[168:171], v[228:231], v[6:9]
	v_mfma_f32_16x16x32_bf16 v[2:5], v[176:179], v[228:231], v[2:5]
	s_setprio 0
	s_barrier
	s_add_i32 s12, 0, 0x18000
	s_add_i32 s13, 0, 0x1c000
	v_add_u32_e32 v160, s12, v216
	v_add_u32_e32 v176, s13, v216
	ds_read_b128 v[148:151], v160
	ds_read_b128 v[152:155], v160 offset:1024
	ds_read_b128 v[156:159], v160 offset:2048
	ds_read_b128 v[160:163], v160 offset:3072
	ds_read_b128 v[164:167], v176
	ds_read_b128 v[168:171], v176 offset:1024
	ds_read_b128 v[172:175], v176 offset:2048
	ds_read_b128 v[176:179], v176 offset:3072
	s_add_u32 s10, s26, 0x200000
	s_addc_u32 s11, s27, 0
	s_mov_b32 m0, s66
	v_lshl_add_u64 v[238:239], s[10:11], 0, v[0:1]
	ds_read_b128 v[180:183], v218 offset:32768
	ds_read_b128 v[184:187], v218 offset:33792
	ds_read_b128 v[188:191], v218 offset:34816
	ds_read_b128 v[192:195], v218 offset:35840
	ds_read_b128 v[196:199], v218 offset:36864
	ds_read_b128 v[220:223], v218 offset:37888
	ds_read_b128 v[224:227], v218 offset:38912
	ds_read_b128 v[228:231], v218 offset:39936
	global_load_lds_dwordx4 v[238:239], off
	v_lshl_add_u64 v[238:239], s[10:11], 0, v[142:143]
	s_mov_b32 m0, s67
	s_nop 0
	global_load_lds_dwordx4 v[238:239], off
	s_waitcnt vmcnt(8)
	s_waitcnt lgkmcnt(0)
	s_barrier
	s_setprio 1
	v_mfma_f32_16x16x32_bf16 v[126:129], v[148:151], v[180:183], v[126:129]
	v_mfma_f32_16x16x32_bf16 v[122:125], v[156:159], v[180:183], v[122:125]
	v_mfma_f32_16x16x32_bf16 v[110:113], v[148:151], v[188:191], v[110:113]
	v_mfma_f32_16x16x32_bf16 v[106:109], v[156:159], v[188:191], v[106:109]
	v_mfma_f32_16x16x32_bf16 v[94:97], v[148:151], v[196:199], v[94:97]
	v_mfma_f32_16x16x32_bf16 v[90:93], v[156:159], v[196:199], v[90:93]
	v_mfma_f32_16x16x32_bf16 v[78:81], v[148:151], v[224:227], v[78:81]
	v_mfma_f32_16x16x32_bf16 v[74:77], v[156:159], v[224:227], v[74:77]
	v_mfma_f32_16x16x32_bf16 v[126:129], v[152:155], v[184:187], v[126:129]
	v_mfma_f32_16x16x32_bf16 v[122:125], v[160:163], v[184:187], v[122:125]
	v_mfma_f32_16x16x32_bf16 v[110:113], v[152:155], v[192:195], v[110:113]
	v_mfma_f32_16x16x32_bf16 v[106:109], v[160:163], v[192:195], v[106:109]
	v_mfma_f32_16x16x32_bf16 v[94:97], v[152:155], v[220:223], v[94:97]
	v_mfma_f32_16x16x32_bf16 v[90:93], v[160:163], v[220:223], v[90:93]
	v_mfma_f32_16x16x32_bf16 v[78:81], v[152:155], v[228:231], v[78:81]
	v_mfma_f32_16x16x32_bf16 v[74:77], v[160:163], v[228:231], v[74:77]
	v_mfma_f32_16x16x32_bf16 v[118:121], v[164:167], v[180:183], v[118:121]
	v_mfma_f32_16x16x32_bf16 v[114:117], v[172:175], v[180:183], v[114:117]
	v_mfma_f32_16x16x32_bf16 v[102:105], v[164:167], v[188:191], v[102:105]
	v_mfma_f32_16x16x32_bf16 v[98:101], v[172:175], v[188:191], v[98:101]
	v_mfma_f32_16x16x32_bf16 v[86:89], v[164:167], v[196:199], v[86:89]
	v_mfma_f32_16x16x32_bf16 v[82:85], v[172:175], v[196:199], v[82:85]
	v_mfma_f32_16x16x32_bf16 v[70:73], v[164:167], v[224:227], v[70:73]
	v_mfma_f32_16x16x32_bf16 v[66:69], v[172:175], v[224:227], v[66:69]
	v_mfma_f32_16x16x32_bf16 v[118:121], v[168:171], v[184:187], v[118:121]
	v_mfma_f32_16x16x32_bf16 v[114:117], v[176:179], v[184:187], v[114:117]
	v_mfma_f32_16x16x32_bf16 v[102:105], v[168:171], v[192:195], v[102:105]
	v_mfma_f32_16x16x32_bf16 v[98:101], v[176:179], v[192:195], v[98:101]
	v_mfma_f32_16x16x32_bf16 v[86:89], v[168:171], v[220:223], v[86:89]
	v_mfma_f32_16x16x32_bf16 v[82:85], v[176:179], v[220:223], v[82:85]
	v_mfma_f32_16x16x32_bf16 v[70:73], v[168:171], v[228:231], v[70:73]
	v_mfma_f32_16x16x32_bf16 v[66:69], v[176:179], v[228:231], v[66:69]
	s_setprio 0
	s_barrier
; __device__ __forceinline__ unsigned cvt_pk_bf16(float lo, float hi) { unsigned r; asm volatile("v_cvt_pk_bf16_f32 %0, %1, %2" : "=v"(r) : "v"(lo), "v"(hi)); return r; }
; #define PG8_WAIT_V(n) asm volatile("s_waitcnt vmcnt(" #n ")" ::: "memory")
; #define PG8_BAR __builtin_amdgcn_s_barrier()
;     __device__ __forceinline__ void operator()(const f32x4 (&acc)[2][2][4][2], const Unit& u, int wr, int wc, int fr, int fq) const {
;         const int row0 = u.pm * BM + wr * 64 + fr; const int col0 = u.pn * BM + wc * 32 + 4 * fq;
; #pragma unroll
;         for (int ai = 0; ai < 2; ++ai) {
;             u32x2 bv[4][2][2];
; #pragma unroll
;             for (int m = 0; m < 4; ++m) { const size_t off = (size_t)(row0 + ai * HALF + m * 16) * ldc + col0;
; #pragma unroll
;                 for (int bj = 0; bj < 2; ++bj)
; #pragma unroll
;                     for (int n = 0; n < 2; ++n) bv[m][bj][n] = *(const u32x2*)(xb + off + bj * HALF + n * 16); }
;             asm volatile("" ::: "memory");
; #pragma unroll
;             for (int m = 0; m < 4; ++m) {
;                 const int row = row0 + ai * HALF + m * 16;
;                 const size_t off = (size_t)row * ldc + col0;
;                 float s = 0.f;
; #pragma unroll
;                 for (int bj = 0; bj < 2; ++bj)
; #pragma unroll
;                     for (int n = 0; n < 2; ++n) {
;                         const size_t c = off + bj * HALF + n * 16;
;                         const u32x2 w0 = bv[m][bj][n];
;                         const f32x4 b = {__uint_as_float(w0.x << 16), __uint_as_float(w0.x & 0xffff0000u), __uint_as_float(w0.y << 16), __uint_as_float(w0.y & 0xffff0000u)};
;                         const f32x4 o = b + acc[ai][bj][m][n];
;                         if (fin) { *(f32x4*)(outf + c) = o; }
;                         else { u32x2 w; w.x = cvt_pk_bf16(o[0], o[1]); w.y = cvt_pk_bf16(o[2], o[3]); *(u32x2*)(xb + c) = w;
; template <class Epi, class Sched, bool ALIGN_EPI = false, bool SP2 = false>
; __device__ __forceinline__ void gemm_phase(PG8_LAS unsigned char* lds, const Gemm g, const Sched& S, const Epi& E) {
;     ...
;             PG8_LDA(At, 1, 1); PG8_STAGE(PG8_SB(1, 0), b3, voffB); PG8_STAGE(PG8_SB(1, 1), b3 + hstep, voffB); PG8_STAGE(PG8_SA(1, 0), a3, voffA);
;             PG8_WAIT_V(8); PG8_WAIT_L(0); PG8_BAR; PG8_MMA(1, 0, At, B0); PG8_MMA(1, 1, At, B1); PG8_BAR; PG8_SCHED;
	s_add_i32 s10, s12, s63
	v_lshl_add_u64 v[200:201], v[200:201], 0, s[30:31]
	s_mov_b32 m0, s10
	ds_read_b128 v[180:183], v218 offset:49152
	ds_read_b128 v[184:187], v218 offset:50176
	ds_read_b128 v[188:191], v218 offset:51200
	ds_read_b128 v[192:195], v218 offset:52224
	ds_read_b128 v[196:199], v218 offset:53248
	ds_read_b128 v[220:223], v218 offset:54272
	ds_read_b128 v[224:227], v218 offset:55296
	ds_read_b128 v[228:231], v218 offset:56320
	global_load_lds_dwordx4 v[200:201], off
	s_add_i32 m0, s10, 0x2000
	s_add_u32 s10, s24, 0x200080
	v_lshl_add_u64 v[200:201], v[232:233], 0, s[30:31]
	s_addc_u32 s11, s25, 0
	s_add_i32 s12, s13, s63
	global_load_lds_dwordx4 v[200:201], off
	v_lshl_add_u64 v[200:201], s[10:11], 0, v[0:1]
	s_mov_b32 m0, s12
	s_nop 0
	global_load_lds_dwordx4 v[200:201], off
	v_lshl_add_u64 v[200:201], s[10:11], 0, v[142:143]
	s_add_i32 m0, s12, 0x2000
	s_nop 0
	global_load_lds_dwordx4 v[200:201], off
	v_lshl_add_u64 v[200:201], v[234:235], 0, s[30:31]
	s_mov_b32 m0, s68
	s_nop 0
	global_load_lds_dwordx4 v[200:201], off
	v_lshl_add_u64 v[200:201], v[236:237], 0, s[30:31]
	s_mov_b32 m0, s69
	s_nop 0
	global_load_lds_dwordx4 v[200:201], off
	s_waitcnt vmcnt(8)
	s_waitcnt lgkmcnt(0)
	s_barrier
	s_setprio 1
	v_mfma_f32_16x16x32_bf16 v[62:65], v[148:151], v[180:183], v[62:65]
	v_mfma_f32_16x16x32_bf16 v[58:61], v[156:159], v[180:183], v[58:61]
	v_mfma_f32_16x16x32_bf16 v[46:49], v[148:151], v[188:191], v[46:49]
	v_mfma_f32_16x16x32_bf16 v[42:45], v[156:159], v[188:191], v[42:45]
	v_mfma_f32_16x16x32_bf16 v[30:33], v[148:151], v[196:199], v[30:33]
	v_mfma_f32_16x16x32_bf16 v[26:29], v[156:159], v[196:199], v[26:29]
	v_mfma_f32_16x16x32_bf16 v[14:17], v[148:151], v[224:227], v[14:17]
	v_mfma_f32_16x16x32_bf16 v[10:13], v[156:159], v[224:227], v[10:13]
	v_mfma_f32_16x16x32_bf16 v[62:65], v[152:155], v[184:187], v[62:65]
	v_mfma_f32_16x16x32_bf16 v[58:61], v[160:163], v[184:187], v[58:61]
	v_mfma_f32_16x16x32_bf16 v[46:49], v[152:155], v[192:195], v[46:49]
	v_mfma_f32_16x16x32_bf16 v[42:45], v[160:163], v[192:195], v[42:45]
	v_mfma_f32_16x16x32_bf16 v[30:33], v[152:155], v[220:223], v[30:33]
	v_mfma_f32_16x16x32_bf16 v[26:29], v[160:163], v[220:223], v[26:29]
	v_mfma_f32_16x16x32_bf16 v[14:17], v[152:155], v[228:231], v[14:17]
	v_mfma_f32_16x16x32_bf16 v[10:13], v[160:163], v[228:231], v[10:13]
	v_mfma_f32_16x16x32_bf16 v[54:57], v[164:167], v[180:183], v[54:57]
	v_mfma_f32_16x16x32_bf16 v[50:53], v[172:175], v[180:183], v[50:53]
	v_mfma_f32_16x16x32_bf16 v[38:41], v[164:167], v[188:191], v[38:41]
	v_mfma_f32_16x16x32_bf16 v[34:37], v[172:175], v[188:191], v[34:37]
	v_mfma_f32_16x16x32_bf16 v[22:25], v[164:167], v[196:199], v[22:25]
	v_mfma_f32_16x16x32_bf16 v[18:21], v[172:175], v[196:199], v[18:21]
	v_mfma_f32_16x16x32_bf16 v[6:9], v[164:167], v[224:227], v[6:9]
	v_mfma_f32_16x16x32_bf16 v[2:5], v[172:175], v[224:227], v[2:5]
	v_mfma_f32_16x16x32_bf16 v[54:57], v[168:171], v[184:187], v[54:57]
	v_mfma_f32_16x16x32_bf16 v[50:53], v[176:179], v[184:187], v[50:53]
	v_mfma_f32_16x16x32_bf16 v[38:41], v[168:171], v[192:195], v[38:41]
	v_mfma_f32_16x16x32_bf16 v[34:37], v[176:179], v[192:195], v[34:37]
	v_mfma_f32_16x16x32_bf16 v[22:25], v[168:171], v[220:223], v[22:25]
	v_mfma_f32_16x16x32_bf16 v[18:21], v[176:179], v[220:223], v[18:21]
	v_mfma_f32_16x16x32_bf16 v[6:9], v[168:171], v[228:231], v[6:9]
	v_mfma_f32_16x16x32_bf16 v[2:5], v[176:179], v[228:231], v[2:5]
	s_setprio 0
	s_barrier
	s_add_i32 s22, s22, 2
	s_add_u32 s14, s14, 0x100
	s_addc_u32 s15, s15, 0
	s_cmpk_gt_u32 s22, 0x7d
	s_mov_b64 s[16:17], s[18:19]
	s_cbranch_scc0 .LBB0_758
	v_lshl_add_u32 v152, s4, 8, v215
	v_lshl_or_b32 v148, s2, 8, v217
	v_ashrrev_i32_e32 v149, 31, v148
	v_ashrrev_i32_e32 v153, 31, v152
	v_or_b32_e32 v176, 16, v152
	v_lshl_add_u64 v[150:151], v[148:149], 1, s[50:51]
	v_lshlrev_b64 v[154:155], 12, v[152:153]
	v_ashrrev_i32_e32 v177, 31, v176
	v_or_b32_e32 v164, 32, v152
	v_lshl_add_u64 v[198:199], v[150:151], 0, v[154:155]
	v_lshlrev_b64 v[154:155], 12, v[176:177]
	v_ashrrev_i32_e32 v165, 31, v164
	v_lshl_add_u64 v[186:187], v[150:151], 0, v[154:155]
	v_lshlrev_b64 v[154:155], 12, v[164:165]
	v_lshl_add_u64 v[174:175], v[150:151], 0, v[154:155]
	v_or_b32_e32 v154, 48, v152
	v_ashrrev_i32_e32 v155, 31, v154
	v_lshlrev_b64 v[156:157], 12, v[154:155]
	v_lshl_add_u64 v[162:163], v[150:151], 0, v[156:157]
	global_load_dwordx2 v[192:193], v[198:199], off
	global_load_dwordx2 v[196:197], v[198:199], off offset:32
	global_load_dwordx2 v[194:195], v[198:199], off offset:256
	global_load_dwordx2 v[190:191], v[198:199], off offset:288
	global_load_dwordx2 v[188:189], v[186:187], off
	global_load_dwordx2 v[184:185], v[186:187], off offset:32
	global_load_dwordx2 v[182:183], v[186:187], off offset:256
	global_load_dwordx2 v[180:181], v[186:187], off offset:288
	global_load_dwordx2 v[178:179], v[174:175], off
	global_load_dwordx2 v[172:173], v[174:175], off offset:32
	global_load_dwordx2 v[170:171], v[174:175], off offset:256
	global_load_dwordx2 v[168:169], v[174:175], off offset:288
	global_load_dwordx2 v[166:167], v[162:163], off
	global_load_dwordx2 v[160:161], v[162:163], off offset:32
	global_load_dwordx2 v[158:159], v[162:163], off offset:256
	global_load_dwordx2 v[156:157], v[162:163], off offset:288
	v_readlane_b32 s4, v244, 52
	v_readlane_b32 s5, v244, 53
	s_mov_b64 s[16:17], -1
	s_andn2_b64 vcc, exec, s[4:5]
	v_cndmask_b32_e64 v200, 0, 1, s[4:5]
	v_cmp_ne_u32_e64 s[44:45], 1, v200
	v_lshlrev_b64 v[200:201], 11, v[152:153]
	v_lshl_add_u64 v[200:201], v[200:201], 0, v[148:149]
	s_waitcnt vmcnt(0)
	v_lshlrev_b32_e32 v220, 16, v192
	v_and_b32_e32 v221, 0xffff0000, v192
	v_lshlrev_b32_e32 v192, 16, v193
	v_and_b32_e32 v193, 0xffff0000, v193
	v_pk_add_f32 v[128:129], v[128:129], v[192:193]
	v_pk_add_f32 v[126:127], v[126:127], v[220:221]
	v_lshl_add_u64 v[192:193], v[200:201], 2, s[48:49]
	s_cbranch_vccnz .LBB0_761
	s_mov_b64 s[16:17], 0
	global_store_dwordx4 v[192:193], v[126:129], off
